# v24 + GEMM MMA blocks issue their 16 MFMAs in snake order (one operand changes per MFMA instead of up to two)
# baseline (speedup 1.0000x reference)
.LBB0_90:
	ds_read_b128 v[130:133], v179
	ds_read_b128 v[134:137], v179 offset:1024
	ds_read_b128 v[138:141], v179 offset:2048
	ds_read_b128 v[142:145], v179 offset:3072
	ds_read_b128 v[166:169], v180
	ds_read_b128 v[170:173], v180 offset:1024
	ds_read_b128 v[184:187], v180 offset:2048
	ds_read_b128 v[188:191], v180 offset:3072
	s_add_u32 s42, s40, 0xfff80080
	s_addc_u32 s43, s41, -1
	s_cmp_eq_u32 s77, 28
	s_cselect_b32 s45, s31, s43
	s_cselect_b32 s44, s39, s42
	s_cselect_b32 s43, s29, s76
	s_cselect_b32 s42, s74, s75
	v_lshl_add_u64 v[224:225], s[40:41], 0, v[158:159]
	s_add_i32 m0, s52, 0xc000
	ds_read_b128 v[192:195], v181
	ds_read_b128 v[196:199], v181 offset:1024
	ds_read_b128 v[200:203], v181 offset:2048
	ds_read_b128 v[204:207], v181 offset:3072
	ds_read_b128 v[208:211], v181 offset:4096
	ds_read_b128 v[212:215], v181 offset:5120
	ds_read_b128 v[216:219], v181 offset:6144
	ds_read_b128 v[220:223], v181 offset:7168
	global_load_lds_dwordx4 v[224:225], off
	v_lshl_add_u64 v[224:225], s[40:41], 0, v[160:161]
	s_add_i32 m0, s52, 0xe000
	s_nop 0
	global_load_lds_dwordx4 v[224:225], off
	s_waitcnt vmcnt(8)
	s_waitcnt lgkmcnt(0)
	s_barrier
	s_setprio 1
	s_waitcnt lgkmcnt(0)
	v_mfma_f32_16x16x32_bf16 v[126:129], v[130:133], v[192:195], v[126:129]
	v_mfma_f32_16x16x32_bf16 v[122:125], v[138:141], v[192:195], v[122:125]
	v_mfma_f32_16x16x32_bf16 v[110:113], v[138:141], v[200:203], v[110:113]
	v_mfma_f32_16x16x32_bf16 v[118:121], v[130:133], v[200:203], v[118:121]
	v_mfma_f32_16x16x32_bf16 v[102:105], v[130:133], v[208:211], v[102:105]
	v_mfma_f32_16x16x32_bf16 v[94:97], v[138:141], v[208:211], v[94:97]
	v_mfma_f32_16x16x32_bf16 v[78:81], v[138:141], v[216:219], v[78:81]
	v_mfma_f32_16x16x32_bf16 v[86:89], v[130:133], v[216:219], v[86:89]
	v_mfma_f32_16x16x32_bf16 v[126:129], v[134:137], v[196:199], v[126:129]
	v_mfma_f32_16x16x32_bf16 v[122:125], v[142:145], v[196:199], v[122:125]
	v_mfma_f32_16x16x32_bf16 v[110:113], v[142:145], v[204:207], v[110:113]
	v_mfma_f32_16x16x32_bf16 v[118:121], v[134:137], v[204:207], v[118:121]
	v_mfma_f32_16x16x32_bf16 v[102:105], v[134:137], v[212:215], v[102:105]
	v_mfma_f32_16x16x32_bf16 v[94:97], v[142:145], v[212:215], v[94:97]
	v_mfma_f32_16x16x32_bf16 v[78:81], v[142:145], v[220:223], v[78:81]
	v_mfma_f32_16x16x32_bf16 v[86:89], v[134:137], v[220:223], v[86:89]
	s_setprio 0
	s_setprio 1
	v_mfma_f32_16x16x32_bf16 v[114:117], v[166:169], v[192:195], v[114:117]
	v_mfma_f32_16x16x32_bf16 v[106:109], v[184:187], v[192:195], v[106:109]
	v_mfma_f32_16x16x32_bf16 v[90:93], v[184:187], v[200:203], v[90:93]
	v_mfma_f32_16x16x32_bf16 v[98:101], v[166:169], v[200:203], v[98:101]
	v_mfma_f32_16x16x32_bf16 v[82:85], v[166:169], v[208:211], v[82:85]
	v_mfma_f32_16x16x32_bf16 v[74:77], v[184:187], v[208:211], v[74:77]
	v_mfma_f32_16x16x32_bf16 v[66:69], v[184:187], v[216:219], v[66:69]
	v_mfma_f32_16x16x32_bf16 v[70:73], v[166:169], v[216:219], v[70:73]
	v_mfma_f32_16x16x32_bf16 v[114:117], v[170:173], v[196:199], v[114:117]
	v_mfma_f32_16x16x32_bf16 v[106:109], v[188:191], v[196:199], v[106:109]
	v_mfma_f32_16x16x32_bf16 v[90:93], v[188:191], v[204:207], v[90:93]
	v_mfma_f32_16x16x32_bf16 v[98:101], v[170:173], v[204:207], v[98:101]
	v_mfma_f32_16x16x32_bf16 v[82:85], v[170:173], v[212:215], v[82:85]
	v_mfma_f32_16x16x32_bf16 v[74:77], v[188:191], v[212:215], v[74:77]
	v_mfma_f32_16x16x32_bf16 v[66:69], v[188:191], v[220:223], v[66:69]
	v_mfma_f32_16x16x32_bf16 v[70:73], v[170:173], v[220:223], v[70:73]
	s_setprio 0
	s_barrier
	s_add_i32 s78, s63, s49
	v_lshl_add_u64 v[224:225], s[42:43], 0, v[150:151]
	s_mov_b32 m0, s78
	ds_read_b128 v[192:195], v181 offset:16384
	ds_read_b128 v[196:199], v181 offset:17408
	ds_read_b128 v[200:203], v181 offset:18432
	ds_read_b128 v[204:207], v181 offset:19456
	ds_read_b128 v[208:211], v181 offset:20480
	ds_read_b128 v[212:215], v181 offset:21504
	ds_read_b128 v[216:219], v181 offset:22528
	ds_read_b128 v[220:223], v181 offset:23552
	global_load_lds_dwordx4 v[224:225], off
	s_add_i32 m0, s78, 0x2000
	s_add_u32 s78, s42, 0x80000
	v_lshl_add_u64 v[226:227], s[42:43], 0, v[146:147]
	s_addc_u32 s79, s43, 0
	s_add_i32 s80, s64, s49
	global_load_lds_dwordx4 v[226:227], off
	v_lshl_add_u64 v[228:229], s[78:79], 0, v[150:151]
	s_mov_b32 m0, s80
	v_lshl_add_u64 v[230:231], s[44:45], 0, v[148:149]
	global_load_lds_dwordx4 v[228:229], off
	v_lshl_add_u64 v[228:229], s[78:79], 0, v[146:147]
	s_add_i32 m0, s80, 0x2000
	s_nop 0
	global_load_lds_dwordx4 v[228:229], off
	v_lshl_add_u64 v[228:229], s[44:45], 0, v[152:153]
	s_mov_b32 m0, s52
	s_nop 0
	global_load_lds_dwordx4 v[228:229], off
	s_mov_b32 m0, s53
	s_nop 0
	global_load_lds_dwordx4 v[230:231], off
	s_waitcnt vmcnt(8)
	s_waitcnt lgkmcnt(0)
	s_barrier
	s_setprio 1
	s_waitcnt lgkmcnt(0)
	v_mfma_f32_16x16x32_bf16 v[62:65], v[130:133], v[192:195], v[62:65]
	v_mfma_f32_16x16x32_bf16 v[58:61], v[138:141], v[192:195], v[58:61]
	v_mfma_f32_16x16x32_bf16 v[46:49], v[138:141], v[200:203], v[46:49]
	v_mfma_f32_16x16x32_bf16 v[54:57], v[130:133], v[200:203], v[54:57]
	v_mfma_f32_16x16x32_bf16 v[38:41], v[130:133], v[208:211], v[38:41]
	v_mfma_f32_16x16x32_bf16 v[30:33], v[138:141], v[208:211], v[30:33]
	v_mfma_f32_16x16x32_bf16 v[14:17], v[138:141], v[216:219], v[14:17]
	v_mfma_f32_16x16x32_bf16 v[22:25], v[130:133], v[216:219], v[22:25]
	v_mfma_f32_16x16x32_bf16 v[62:65], v[134:137], v[196:199], v[62:65]
	v_mfma_f32_16x16x32_bf16 v[58:61], v[142:145], v[196:199], v[58:61]
	v_mfma_f32_16x16x32_bf16 v[46:49], v[142:145], v[204:207], v[46:49]
	v_mfma_f32_16x16x32_bf16 v[54:57], v[134:137], v[204:207], v[54:57]
	v_mfma_f32_16x16x32_bf16 v[38:41], v[134:137], v[212:215], v[38:41]
	v_mfma_f32_16x16x32_bf16 v[30:33], v[142:145], v[212:215], v[30:33]
	v_mfma_f32_16x16x32_bf16 v[14:17], v[142:145], v[220:223], v[14:17]
	v_mfma_f32_16x16x32_bf16 v[22:25], v[134:137], v[220:223], v[22:25]
	s_setprio 0
	s_setprio 1
	v_mfma_f32_16x16x32_bf16 v[50:53], v[166:169], v[192:195], v[50:53]
	v_mfma_f32_16x16x32_bf16 v[42:45], v[184:187], v[192:195], v[42:45]
	v_mfma_f32_16x16x32_bf16 v[26:29], v[184:187], v[200:203], v[26:29]
	v_mfma_f32_16x16x32_bf16 v[34:37], v[166:169], v[200:203], v[34:37]
	v_mfma_f32_16x16x32_bf16 v[18:21], v[166:169], v[208:211], v[18:21]
	v_mfma_f32_16x16x32_bf16 v[10:13], v[184:187], v[208:211], v[10:13]
	v_mfma_f32_16x16x32_bf16 v[2:5], v[184:187], v[216:219], v[2:5]
	v_mfma_f32_16x16x32_bf16 v[6:9], v[166:169], v[216:219], v[6:9]
	v_mfma_f32_16x16x32_bf16 v[50:53], v[170:173], v[196:199], v[50:53]
	v_mfma_f32_16x16x32_bf16 v[42:45], v[188:191], v[196:199], v[42:45]
	v_mfma_f32_16x16x32_bf16 v[26:29], v[188:191], v[204:207], v[26:29]
	v_mfma_f32_16x16x32_bf16 v[34:37], v[170:173], v[204:207], v[34:37]
	v_mfma_f32_16x16x32_bf16 v[18:21], v[170:173], v[212:215], v[18:21]
	v_mfma_f32_16x16x32_bf16 v[10:13], v[188:191], v[212:215], v[10:13]
	v_mfma_f32_16x16x32_bf16 v[2:5], v[188:191], v[220:223], v[2:5]
	v_mfma_f32_16x16x32_bf16 v[6:9], v[170:173], v[220:223], v[6:9]
	s_setprio 0
	s_barrier
	s_add_i32 s78, 0, 0x18000
	s_add_i32 s79, 0, 0x1c000
	v_add_u32_e32 v142, s78, v174
	v_add_u32_e32 v154, s79, v174
	ds_read_b128 v[130:133], v142
	ds_read_b128 v[134:137], v142 offset:1024
	ds_read_b128 v[138:141], v142 offset:2048
	ds_read_b128 v[142:145], v142 offset:3072
	ds_read_b128 v[166:169], v154
	ds_read_b128 v[170:173], v154 offset:1024
	ds_read_b128 v[184:187], v154 offset:2048
	ds_read_b128 v[188:191], v154 offset:3072
	s_add_u32 s44, s44, 0x80000
	s_addc_u32 s45, s45, 0
	s_mov_b32 m0, s54
	v_lshl_add_u64 v[232:233], s[44:45], 0, v[152:153]
	ds_read_b128 v[192:195], v181 offset:32768
	ds_read_b128 v[196:199], v181 offset:33792
	ds_read_b128 v[200:203], v181 offset:34816
	ds_read_b128 v[204:207], v181 offset:35840
	ds_read_b128 v[208:211], v181 offset:36864
	ds_read_b128 v[212:215], v181 offset:37888
	ds_read_b128 v[216:219], v181 offset:38912
	ds_read_b128 v[220:223], v181 offset:39936
	global_load_lds_dwordx4 v[232:233], off
	v_lshl_add_u64 v[232:233], s[44:45], 0, v[148:149]
	s_mov_b32 m0, s55
	s_nop 0
	global_load_lds_dwordx4 v[232:233], off
	s_waitcnt vmcnt(8)
	s_waitcnt lgkmcnt(0)
	s_barrier
	s_setprio 1
	s_waitcnt lgkmcnt(0)
	v_mfma_f32_16x16x32_bf16 v[126:129], v[130:133], v[192:195], v[126:129]
	v_mfma_f32_16x16x32_bf16 v[122:125], v[138:141], v[192:195], v[122:125]
	v_mfma_f32_16x16x32_bf16 v[110:113], v[138:141], v[200:203], v[110:113]
	v_mfma_f32_16x16x32_bf16 v[118:121], v[130:133], v[200:203], v[118:121]
	v_mfma_f32_16x16x32_bf16 v[102:105], v[130:133], v[208:211], v[102:105]
	v_mfma_f32_16x16x32_bf16 v[94:97], v[138:141], v[208:211], v[94:97]
	v_mfma_f32_16x16x32_bf16 v[78:81], v[138:141], v[216:219], v[78:81]
	v_mfma_f32_16x16x32_bf16 v[86:89], v[130:133], v[216:219], v[86:89]
	v_mfma_f32_16x16x32_bf16 v[126:129], v[134:137], v[196:199], v[126:129]
	v_mfma_f32_16x16x32_bf16 v[122:125], v[142:145], v[196:199], v[122:125]
	v_mfma_f32_16x16x32_bf16 v[110:113], v[142:145], v[204:207], v[110:113]
	v_mfma_f32_16x16x32_bf16 v[118:121], v[134:137], v[204:207], v[118:121]
	v_mfma_f32_16x16x32_bf16 v[102:105], v[134:137], v[212:215], v[102:105]
	v_mfma_f32_16x16x32_bf16 v[94:97], v[142:145], v[212:215], v[94:97]
	v_mfma_f32_16x16x32_bf16 v[78:81], v[142:145], v[220:223], v[78:81]
	v_mfma_f32_16x16x32_bf16 v[86:89], v[134:137], v[220:223], v[86:89]
	s_setprio 0
	s_setprio 1
	v_mfma_f32_16x16x32_bf16 v[114:117], v[166:169], v[192:195], v[114:117]
	v_mfma_f32_16x16x32_bf16 v[106:109], v[184:187], v[192:195], v[106:109]
	v_mfma_f32_16x16x32_bf16 v[90:93], v[184:187], v[200:203], v[90:93]
	v_mfma_f32_16x16x32_bf16 v[98:101], v[166:169], v[200:203], v[98:101]
	v_mfma_f32_16x16x32_bf16 v[82:85], v[166:169], v[208:211], v[82:85]
	v_mfma_f32_16x16x32_bf16 v[74:77], v[184:187], v[208:211], v[74:77]
	v_mfma_f32_16x16x32_bf16 v[66:69], v[184:187], v[216:219], v[66:69]
	v_mfma_f32_16x16x32_bf16 v[70:73], v[166:169], v[216:219], v[70:73]
	v_mfma_f32_16x16x32_bf16 v[114:117], v[170:173], v[196:199], v[114:117]
	v_mfma_f32_16x16x32_bf16 v[106:109], v[188:191], v[196:199], v[106:109]
	v_mfma_f32_16x16x32_bf16 v[90:93], v[188:191], v[204:207], v[90:93]
	v_mfma_f32_16x16x32_bf16 v[98:101], v[170:173], v[204:207], v[98:101]
	v_mfma_f32_16x16x32_bf16 v[82:85], v[170:173], v[212:215], v[82:85]
	v_mfma_f32_16x16x32_bf16 v[74:77], v[188:191], v[212:215], v[74:77]
	v_mfma_f32_16x16x32_bf16 v[66:69], v[188:191], v[220:223], v[66:69]
	v_mfma_f32_16x16x32_bf16 v[70:73], v[170:173], v[220:223], v[70:73]
	s_setprio 0
	s_barrier
	s_add_i32 s44, s78, s49
	v_lshl_add_u64 v[224:225], v[224:225], 0, s[10:11]
	s_mov_b32 m0, s44
	ds_read_b128 v[192:195], v181 offset:49152
	ds_read_b128 v[196:199], v181 offset:50176
	ds_read_b128 v[200:203], v181 offset:51200
	ds_read_b128 v[204:207], v181 offset:52224
	ds_read_b128 v[208:211], v181 offset:53248
	ds_read_b128 v[212:215], v181 offset:54272
	ds_read_b128 v[216:219], v181 offset:55296
	ds_read_b128 v[220:223], v181 offset:56320
	global_load_lds_dwordx4 v[224:225], off
	s_add_i32 m0, s44, 0x2000
	s_add_u32 s42, s42, 0x80080
	v_lshl_add_u64 v[224:225], v[226:227], 0, s[10:11]
	s_addc_u32 s43, s43, 0
	s_add_i32 s44, s79, s49
	global_load_lds_dwordx4 v[224:225], off
	v_lshl_add_u64 v[224:225], s[42:43], 0, v[150:151]
	s_mov_b32 m0, s44
	s_nop 0
	global_load_lds_dwordx4 v[224:225], off
	v_lshl_add_u64 v[224:225], s[42:43], 0, v[146:147]
	s_add_i32 m0, s44, 0x2000
	s_nop 0
	global_load_lds_dwordx4 v[224:225], off
	v_lshl_add_u64 v[224:225], v[228:229], 0, s[10:11]
	s_mov_b32 m0, s59
	s_nop 0
	global_load_lds_dwordx4 v[224:225], off
	v_lshl_add_u64 v[224:225], v[230:231], 0, s[10:11]
	s_mov_b32 m0, s60
	s_nop 0
	global_load_lds_dwordx4 v[224:225], off
	s_waitcnt vmcnt(8)
	s_waitcnt lgkmcnt(0)
	s_barrier
	s_setprio 1
	s_waitcnt lgkmcnt(0)
	v_mfma_f32_16x16x32_bf16 v[62:65], v[130:133], v[192:195], v[62:65]
	v_mfma_f32_16x16x32_bf16 v[58:61], v[138:141], v[192:195], v[58:61]
	v_mfma_f32_16x16x32_bf16 v[46:49], v[138:141], v[200:203], v[46:49]
	v_mfma_f32_16x16x32_bf16 v[54:57], v[130:133], v[200:203], v[54:57]
	v_mfma_f32_16x16x32_bf16 v[38:41], v[130:133], v[208:211], v[38:41]
	v_mfma_f32_16x16x32_bf16 v[30:33], v[138:141], v[208:211], v[30:33]
	v_mfma_f32_16x16x32_bf16 v[14:17], v[138:141], v[216:219], v[14:17]
	v_mfma_f32_16x16x32_bf16 v[22:25], v[130:133], v[216:219], v[22:25]
	v_mfma_f32_16x16x32_bf16 v[62:65], v[134:137], v[196:199], v[62:65]
	v_mfma_f32_16x16x32_bf16 v[58:61], v[142:145], v[196:199], v[58:61]
	v_mfma_f32_16x16x32_bf16 v[46:49], v[142:145], v[204:207], v[46:49]
	v_mfma_f32_16x16x32_bf16 v[54:57], v[134:137], v[204:207], v[54:57]
	v_mfma_f32_16x16x32_bf16 v[38:41], v[134:137], v[212:215], v[38:41]
	v_mfma_f32_16x16x32_bf16 v[30:33], v[142:145], v[212:215], v[30:33]
	v_mfma_f32_16x16x32_bf16 v[14:17], v[142:145], v[220:223], v[14:17]
	v_mfma_f32_16x16x32_bf16 v[22:25], v[134:137], v[220:223], v[22:25]
	s_setprio 0
	s_setprio 1
	v_mfma_f32_16x16x32_bf16 v[50:53], v[166:169], v[192:195], v[50:53]
	v_mfma_f32_16x16x32_bf16 v[42:45], v[184:187], v[192:195], v[42:45]
	v_mfma_f32_16x16x32_bf16 v[26:29], v[184:187], v[200:203], v[26:29]
	v_mfma_f32_16x16x32_bf16 v[34:37], v[166:169], v[200:203], v[34:37]
	v_mfma_f32_16x16x32_bf16 v[18:21], v[166:169], v[208:211], v[18:21]
	v_mfma_f32_16x16x32_bf16 v[10:13], v[184:187], v[208:211], v[10:13]
	v_mfma_f32_16x16x32_bf16 v[2:5], v[184:187], v[216:219], v[2:5]
	v_mfma_f32_16x16x32_bf16 v[6:9], v[166:169], v[216:219], v[6:9]
	v_mfma_f32_16x16x32_bf16 v[50:53], v[170:173], v[196:199], v[50:53]
	v_mfma_f32_16x16x32_bf16 v[42:45], v[188:191], v[196:199], v[42:45]
	v_mfma_f32_16x16x32_bf16 v[26:29], v[188:191], v[204:207], v[26:29]
	v_mfma_f32_16x16x32_bf16 v[34:37], v[170:173], v[204:207], v[34:37]
	v_mfma_f32_16x16x32_bf16 v[18:21], v[170:173], v[212:215], v[18:21]
	v_mfma_f32_16x16x32_bf16 v[10:13], v[188:191], v[212:215], v[10:13]
	v_mfma_f32_16x16x32_bf16 v[2:5], v[188:191], v[220:223], v[2:5]
	v_mfma_f32_16x16x32_bf16 v[6:9], v[170:173], v[220:223], v[6:9]
	s_setprio 0
	s_barrier
	s_add_i32 s77, s77, 2
	s_add_u32 s40, s40, 0x100
	s_addc_u32 s41, s41, 0
	s_add_u32 s75, s75, 0x100
	s_addc_u32 s76, s76, 0
	s_cmp_gt_u32 s77, 29
	s_cbranch_scc0 .LBB0_90
	s_and_b64 vcc, exec, s[12:13]
	s_cbranch_vccnz .LBB0_95
	v_lshl_add_u32 v166, s38, 8, v1
	s_cmp_gt_i32 s73, 11
	s_mov_b64 s[38:39], -1
	s_cbranch_scc1 .LBB0_96

.LBB0_263:
	ds_read_b128 v[154:157], v184
	ds_read_b128 v[158:161], v184 offset:1024
	ds_read_b128 v[162:165], v184 offset:2048
	ds_read_b128 v[166:169], v184 offset:3072
	ds_read_b128 v[188:191], v185
	ds_read_b128 v[192:195], v185 offset:1024
	ds_read_b128 v[196:199], v185 offset:2048
	ds_read_b128 v[200:203], v185 offset:3072
	s_add_u32 s22, s20, 0xfffd0080
	s_addc_u32 s23, s21, -1
	s_cmp_eq_u32 s53, 8
	s_cselect_b32 s25, s1, s23
	s_cselect_b32 s24, s0, s22
	s_cselect_b32 s23, s19, s52
	s_cselect_b32 s22, s18, s51
	v_lshl_add_u64 v[170:171], s[20:21], 0, v[146:147]
	s_add_i32 m0, s31, 0xc000
	ds_read_b128 v[204:207], v186
	ds_read_b128 v[208:211], v186 offset:1024
	ds_read_b128 v[212:215], v186 offset:2048
	ds_read_b128 v[216:219], v186 offset:3072
	ds_read_b128 v[220:223], v186 offset:4096
	ds_read_b128 v[224:227], v186 offset:5120
	ds_read_b128 v[228:231], v186 offset:6144
	ds_read_b128 v[232:235], v186 offset:7168
	global_load_lds_dwordx4 v[170:171], off
	v_lshl_add_u64 v[170:171], s[20:21], 0, v[148:149]
	s_add_i32 m0, s31, 0xe000
	s_nop 0
	global_load_lds_dwordx4 v[170:171], off
	s_waitcnt vmcnt(8)
	s_waitcnt lgkmcnt(0)
	s_barrier
	s_setprio 1
	s_waitcnt lgkmcnt(0)
	v_mfma_f32_16x16x32_bf16 v[126:129], v[154:157], v[204:207], v[126:129]
	v_mfma_f32_16x16x32_bf16 v[122:125], v[162:165], v[204:207], v[122:125]
	v_mfma_f32_16x16x32_bf16 v[110:113], v[162:165], v[212:215], v[110:113]
	v_mfma_f32_16x16x32_bf16 v[118:121], v[154:157], v[212:215], v[118:121]
	v_mfma_f32_16x16x32_bf16 v[102:105], v[154:157], v[220:223], v[102:105]
	v_mfma_f32_16x16x32_bf16 v[94:97], v[162:165], v[220:223], v[94:97]
	v_mfma_f32_16x16x32_bf16 v[78:81], v[162:165], v[228:231], v[78:81]
	v_mfma_f32_16x16x32_bf16 v[86:89], v[154:157], v[228:231], v[86:89]
	v_mfma_f32_16x16x32_bf16 v[126:129], v[158:161], v[208:211], v[126:129]
	v_mfma_f32_16x16x32_bf16 v[122:125], v[166:169], v[208:211], v[122:125]
	v_mfma_f32_16x16x32_bf16 v[110:113], v[166:169], v[216:219], v[110:113]
	v_mfma_f32_16x16x32_bf16 v[118:121], v[158:161], v[216:219], v[118:121]
	v_mfma_f32_16x16x32_bf16 v[102:105], v[158:161], v[224:227], v[102:105]
	v_mfma_f32_16x16x32_bf16 v[94:97], v[166:169], v[224:227], v[94:97]
	v_mfma_f32_16x16x32_bf16 v[78:81], v[166:169], v[232:235], v[78:81]
	v_mfma_f32_16x16x32_bf16 v[86:89], v[158:161], v[232:235], v[86:89]
	s_setprio 0
	s_setprio 1
	v_mfma_f32_16x16x32_bf16 v[114:117], v[188:191], v[204:207], v[114:117]
	v_mfma_f32_16x16x32_bf16 v[106:109], v[196:199], v[204:207], v[106:109]
	v_mfma_f32_16x16x32_bf16 v[90:93], v[196:199], v[212:215], v[90:93]
	v_mfma_f32_16x16x32_bf16 v[98:101], v[188:191], v[212:215], v[98:101]
	v_mfma_f32_16x16x32_bf16 v[82:85], v[188:191], v[220:223], v[82:85]
	v_mfma_f32_16x16x32_bf16 v[74:77], v[196:199], v[220:223], v[74:77]
	v_mfma_f32_16x16x32_bf16 v[66:69], v[196:199], v[228:231], v[66:69]
	v_mfma_f32_16x16x32_bf16 v[70:73], v[188:191], v[228:231], v[70:73]
	v_mfma_f32_16x16x32_bf16 v[114:117], v[192:195], v[208:211], v[114:117]
	v_mfma_f32_16x16x32_bf16 v[106:109], v[200:203], v[208:211], v[106:109]
	v_mfma_f32_16x16x32_bf16 v[90:93], v[200:203], v[216:219], v[90:93]
	v_mfma_f32_16x16x32_bf16 v[98:101], v[192:195], v[216:219], v[98:101]
	v_mfma_f32_16x16x32_bf16 v[82:85], v[192:195], v[224:227], v[82:85]
	v_mfma_f32_16x16x32_bf16 v[74:77], v[200:203], v[224:227], v[74:77]
	v_mfma_f32_16x16x32_bf16 v[66:69], v[200:203], v[232:235], v[66:69]
	v_mfma_f32_16x16x32_bf16 v[70:73], v[192:195], v[232:235], v[70:73]
	s_setprio 0
	s_barrier
	s_add_i32 s54, s42, s29
	v_lshl_add_u64 v[170:171], s[22:23], 0, v[136:137]
	s_mov_b32 m0, s54
	ds_read_b128 v[204:207], v186 offset:16384
	ds_read_b128 v[208:211], v186 offset:17408
	ds_read_b128 v[212:215], v186 offset:18432
	ds_read_b128 v[216:219], v186 offset:19456
	ds_read_b128 v[220:223], v186 offset:20480
	ds_read_b128 v[224:227], v186 offset:21504
	ds_read_b128 v[228:231], v186 offset:22528
	ds_read_b128 v[232:235], v186 offset:23552
	global_load_lds_dwordx4 v[170:171], off
	s_add_i32 m0, s54, 0x2000
	s_add_u32 s54, s22, 0x30000
	v_lshl_add_u64 v[236:237], s[22:23], 0, v[132:133]
	s_addc_u32 s55, s23, 0
	s_add_i32 s56, s43, s29
	global_load_lds_dwordx4 v[236:237], off
	v_lshl_add_u64 v[238:239], s[54:55], 0, v[136:137]
	s_mov_b32 m0, s56
	v_lshl_add_u64 v[240:241], s[24:25], 0, v[134:135]
	global_load_lds_dwordx4 v[238:239], off
	v_lshl_add_u64 v[238:239], s[54:55], 0, v[132:133]
	s_add_i32 m0, s56, 0x2000
	s_nop 0
	global_load_lds_dwordx4 v[238:239], off
	v_lshl_add_u64 v[238:239], s[24:25], 0, v[138:139]
	s_mov_b32 m0, s31
	s_nop 0
	global_load_lds_dwordx4 v[238:239], off
	s_mov_b32 m0, s33
	s_nop 0
	global_load_lds_dwordx4 v[240:241], off
	s_waitcnt vmcnt(8)
	s_waitcnt lgkmcnt(0)
	s_barrier
	s_setprio 1
	s_waitcnt lgkmcnt(0)
	v_mfma_f32_16x16x32_bf16 v[62:65], v[154:157], v[204:207], v[62:65]
	v_mfma_f32_16x16x32_bf16 v[58:61], v[162:165], v[204:207], v[58:61]
	v_mfma_f32_16x16x32_bf16 v[46:49], v[162:165], v[212:215], v[46:49]
	v_mfma_f32_16x16x32_bf16 v[54:57], v[154:157], v[212:215], v[54:57]
	v_mfma_f32_16x16x32_bf16 v[38:41], v[154:157], v[220:223], v[38:41]
	v_mfma_f32_16x16x32_bf16 v[30:33], v[162:165], v[220:223], v[30:33]
	v_mfma_f32_16x16x32_bf16 v[14:17], v[162:165], v[228:231], v[14:17]
	v_mfma_f32_16x16x32_bf16 v[22:25], v[154:157], v[228:231], v[22:25]
	v_mfma_f32_16x16x32_bf16 v[62:65], v[158:161], v[208:211], v[62:65]
	v_mfma_f32_16x16x32_bf16 v[58:61], v[166:169], v[208:211], v[58:61]
	v_mfma_f32_16x16x32_bf16 v[46:49], v[166:169], v[216:219], v[46:49]
	v_mfma_f32_16x16x32_bf16 v[54:57], v[158:161], v[216:219], v[54:57]
	v_mfma_f32_16x16x32_bf16 v[38:41], v[158:161], v[224:227], v[38:41]
	v_mfma_f32_16x16x32_bf16 v[30:33], v[166:169], v[224:227], v[30:33]
	v_mfma_f32_16x16x32_bf16 v[14:17], v[166:169], v[232:235], v[14:17]
	v_mfma_f32_16x16x32_bf16 v[22:25], v[158:161], v[232:235], v[22:25]
	s_setprio 0
	s_setprio 1
	v_mfma_f32_16x16x32_bf16 v[50:53], v[188:191], v[204:207], v[50:53]
	v_mfma_f32_16x16x32_bf16 v[42:45], v[196:199], v[204:207], v[42:45]
	v_mfma_f32_16x16x32_bf16 v[26:29], v[196:199], v[212:215], v[26:29]
	v_mfma_f32_16x16x32_bf16 v[34:37], v[188:191], v[212:215], v[34:37]
	v_mfma_f32_16x16x32_bf16 v[18:21], v[188:191], v[220:223], v[18:21]
	v_mfma_f32_16x16x32_bf16 v[10:13], v[196:199], v[220:223], v[10:13]
	v_mfma_f32_16x16x32_bf16 v[2:5], v[196:199], v[228:231], v[2:5]
	v_mfma_f32_16x16x32_bf16 v[6:9], v[188:191], v[228:231], v[6:9]
	v_mfma_f32_16x16x32_bf16 v[50:53], v[192:195], v[208:211], v[50:53]
	v_mfma_f32_16x16x32_bf16 v[42:45], v[200:203], v[208:211], v[42:45]
	v_mfma_f32_16x16x32_bf16 v[26:29], v[200:203], v[216:219], v[26:29]
	v_mfma_f32_16x16x32_bf16 v[34:37], v[192:195], v[216:219], v[34:37]
	v_mfma_f32_16x16x32_bf16 v[18:21], v[192:195], v[224:227], v[18:21]
	v_mfma_f32_16x16x32_bf16 v[10:13], v[200:203], v[224:227], v[10:13]
	v_mfma_f32_16x16x32_bf16 v[2:5], v[200:203], v[232:235], v[2:5]
	v_mfma_f32_16x16x32_bf16 v[6:9], v[192:195], v[232:235], v[6:9]
	s_setprio 0
	s_barrier
	s_add_i32 s54, 0, 0x18000
	s_add_i32 s55, 0, 0x1c000
	v_add_u32_e32 v166, s54, v183
	v_add_u32_e32 v187, s55, v183
	ds_read_b128 v[154:157], v166
	ds_read_b128 v[158:161], v166 offset:1024
	ds_read_b128 v[162:165], v166 offset:2048
	ds_read_b128 v[166:169], v166 offset:3072
	ds_read_b128 v[188:191], v187
	ds_read_b128 v[192:195], v187 offset:1024
	ds_read_b128 v[196:199], v187 offset:2048
	ds_read_b128 v[200:203], v187 offset:3072
	s_add_u32 s24, s24, 0x30000
	s_addc_u32 s25, s25, 0
	s_mov_b32 m0, s34
	v_lshl_add_u64 v[242:243], s[24:25], 0, v[138:139]
	ds_read_b128 v[204:207], v186 offset:32768
	ds_read_b128 v[208:211], v186 offset:33792
	ds_read_b128 v[212:215], v186 offset:34816
	ds_read_b128 v[216:219], v186 offset:35840
	ds_read_b128 v[220:223], v186 offset:36864
	ds_read_b128 v[224:227], v186 offset:37888
	ds_read_b128 v[228:231], v186 offset:38912
	ds_read_b128 v[232:235], v186 offset:39936
	global_load_lds_dwordx4 v[242:243], off
	v_lshl_add_u64 v[242:243], s[24:25], 0, v[134:135]
	s_mov_b32 m0, s35
	s_nop 0
	global_load_lds_dwordx4 v[242:243], off
	s_waitcnt vmcnt(8)
	s_waitcnt lgkmcnt(0)
	s_barrier
	s_setprio 1
	s_waitcnt lgkmcnt(0)
	v_mfma_f32_16x16x32_bf16 v[126:129], v[154:157], v[204:207], v[126:129]
	v_mfma_f32_16x16x32_bf16 v[122:125], v[162:165], v[204:207], v[122:125]
	v_mfma_f32_16x16x32_bf16 v[110:113], v[162:165], v[212:215], v[110:113]
	v_mfma_f32_16x16x32_bf16 v[118:121], v[154:157], v[212:215], v[118:121]
	v_mfma_f32_16x16x32_bf16 v[102:105], v[154:157], v[220:223], v[102:105]
	v_mfma_f32_16x16x32_bf16 v[94:97], v[162:165], v[220:223], v[94:97]
	v_mfma_f32_16x16x32_bf16 v[78:81], v[162:165], v[228:231], v[78:81]
	v_mfma_f32_16x16x32_bf16 v[86:89], v[154:157], v[228:231], v[86:89]
	v_mfma_f32_16x16x32_bf16 v[126:129], v[158:161], v[208:211], v[126:129]
	v_mfma_f32_16x16x32_bf16 v[122:125], v[166:169], v[208:211], v[122:125]
	v_mfma_f32_16x16x32_bf16 v[110:113], v[166:169], v[216:219], v[110:113]
	v_mfma_f32_16x16x32_bf16 v[118:121], v[158:161], v[216:219], v[118:121]
	v_mfma_f32_16x16x32_bf16 v[102:105], v[158:161], v[224:227], v[102:105]
	v_mfma_f32_16x16x32_bf16 v[94:97], v[166:169], v[224:227], v[94:97]
	v_mfma_f32_16x16x32_bf16 v[78:81], v[166:169], v[232:235], v[78:81]
	v_mfma_f32_16x16x32_bf16 v[86:89], v[158:161], v[232:235], v[86:89]
	s_setprio 0
	s_setprio 1
	v_mfma_f32_16x16x32_bf16 v[114:117], v[188:191], v[204:207], v[114:117]
	v_mfma_f32_16x16x32_bf16 v[106:109], v[196:199], v[204:207], v[106:109]
	v_mfma_f32_16x16x32_bf16 v[90:93], v[196:199], v[212:215], v[90:93]
	v_mfma_f32_16x16x32_bf16 v[98:101], v[188:191], v[212:215], v[98:101]
	v_mfma_f32_16x16x32_bf16 v[82:85], v[188:191], v[220:223], v[82:85]
	v_mfma_f32_16x16x32_bf16 v[74:77], v[196:199], v[220:223], v[74:77]
	v_mfma_f32_16x16x32_bf16 v[66:69], v[196:199], v[228:231], v[66:69]
	v_mfma_f32_16x16x32_bf16 v[70:73], v[188:191], v[228:231], v[70:73]
	v_mfma_f32_16x16x32_bf16 v[114:117], v[192:195], v[208:211], v[114:117]
	v_mfma_f32_16x16x32_bf16 v[106:109], v[200:203], v[208:211], v[106:109]
	v_mfma_f32_16x16x32_bf16 v[90:93], v[200:203], v[216:219], v[90:93]
	v_mfma_f32_16x16x32_bf16 v[98:101], v[192:195], v[216:219], v[98:101]
	v_mfma_f32_16x16x32_bf16 v[82:85], v[192:195], v[224:227], v[82:85]
	v_mfma_f32_16x16x32_bf16 v[74:77], v[200:203], v[224:227], v[74:77]
	v_mfma_f32_16x16x32_bf16 v[66:69], v[200:203], v[232:235], v[66:69]
	v_mfma_f32_16x16x32_bf16 v[70:73], v[192:195], v[232:235], v[70:73]
	s_setprio 0
	s_barrier
	s_add_i32 s24, s54, s29
	v_lshl_add_u64 v[170:171], v[170:171], 0, s[12:13]
	s_mov_b32 m0, s24
	ds_read_b128 v[204:207], v186 offset:49152
	ds_read_b128 v[208:211], v186 offset:50176
	ds_read_b128 v[212:215], v186 offset:51200
	ds_read_b128 v[216:219], v186 offset:52224
	ds_read_b128 v[220:223], v186 offset:53248
	ds_read_b128 v[224:227], v186 offset:54272
	ds_read_b128 v[228:231], v186 offset:55296
	ds_read_b128 v[232:235], v186 offset:56320
	global_load_lds_dwordx4 v[170:171], off
	s_add_i32 m0, s24, 0x2000
	s_add_u32 s22, s22, 0x30080
	v_lshl_add_u64 v[170:171], v[236:237], 0, s[12:13]
	s_addc_u32 s23, s23, 0
	s_add_i32 s24, s55, s29
	global_load_lds_dwordx4 v[170:171], off
	v_lshl_add_u64 v[170:171], s[22:23], 0, v[136:137]
	s_mov_b32 m0, s24
	s_nop 0
	global_load_lds_dwordx4 v[170:171], off
	v_lshl_add_u64 v[170:171], s[22:23], 0, v[132:133]
	s_add_i32 m0, s24, 0x2000
	s_nop 0
	global_load_lds_dwordx4 v[170:171], off
	v_lshl_add_u64 v[170:171], v[238:239], 0, s[12:13]
	s_mov_b32 m0, s36
	s_nop 0
	global_load_lds_dwordx4 v[170:171], off
	v_lshl_add_u64 v[170:171], v[240:241], 0, s[12:13]
	s_mov_b32 m0, s37
	s_nop 0
	global_load_lds_dwordx4 v[170:171], off
	s_waitcnt vmcnt(8)
	s_waitcnt lgkmcnt(0)
	s_barrier
	s_setprio 1
	s_waitcnt lgkmcnt(0)
	v_mfma_f32_16x16x32_bf16 v[62:65], v[154:157], v[204:207], v[62:65]
	v_mfma_f32_16x16x32_bf16 v[58:61], v[162:165], v[204:207], v[58:61]
	v_mfma_f32_16x16x32_bf16 v[46:49], v[162:165], v[212:215], v[46:49]
	v_mfma_f32_16x16x32_bf16 v[54:57], v[154:157], v[212:215], v[54:57]
	v_mfma_f32_16x16x32_bf16 v[38:41], v[154:157], v[220:223], v[38:41]
	v_mfma_f32_16x16x32_bf16 v[30:33], v[162:165], v[220:223], v[30:33]
	v_mfma_f32_16x16x32_bf16 v[14:17], v[162:165], v[228:231], v[14:17]
	v_mfma_f32_16x16x32_bf16 v[22:25], v[154:157], v[228:231], v[22:25]
	v_mfma_f32_16x16x32_bf16 v[62:65], v[158:161], v[208:211], v[62:65]
	v_mfma_f32_16x16x32_bf16 v[58:61], v[166:169], v[208:211], v[58:61]
	v_mfma_f32_16x16x32_bf16 v[46:49], v[166:169], v[216:219], v[46:49]
	v_mfma_f32_16x16x32_bf16 v[54:57], v[158:161], v[216:219], v[54:57]
	v_mfma_f32_16x16x32_bf16 v[38:41], v[158:161], v[224:227], v[38:41]
	v_mfma_f32_16x16x32_bf16 v[30:33], v[166:169], v[224:227], v[30:33]
	v_mfma_f32_16x16x32_bf16 v[14:17], v[166:169], v[232:235], v[14:17]
	v_mfma_f32_16x16x32_bf16 v[22:25], v[158:161], v[232:235], v[22:25]
	s_setprio 0
	s_setprio 1
	v_mfma_f32_16x16x32_bf16 v[50:53], v[188:191], v[204:207], v[50:53]
	v_mfma_f32_16x16x32_bf16 v[42:45], v[196:199], v[204:207], v[42:45]
	v_mfma_f32_16x16x32_bf16 v[26:29], v[196:199], v[212:215], v[26:29]
	v_mfma_f32_16x16x32_bf16 v[34:37], v[188:191], v[212:215], v[34:37]
	v_mfma_f32_16x16x32_bf16 v[18:21], v[188:191], v[220:223], v[18:21]
	v_mfma_f32_16x16x32_bf16 v[10:13], v[196:199], v[220:223], v[10:13]
	v_mfma_f32_16x16x32_bf16 v[2:5], v[196:199], v[228:231], v[2:5]
	v_mfma_f32_16x16x32_bf16 v[6:9], v[188:191], v[228:231], v[6:9]
	v_mfma_f32_16x16x32_bf16 v[50:53], v[192:195], v[208:211], v[50:53]
	v_mfma_f32_16x16x32_bf16 v[42:45], v[200:203], v[208:211], v[42:45]
	v_mfma_f32_16x16x32_bf16 v[26:29], v[200:203], v[216:219], v[26:29]
	v_mfma_f32_16x16x32_bf16 v[34:37], v[192:195], v[216:219], v[34:37]
	v_mfma_f32_16x16x32_bf16 v[18:21], v[192:195], v[224:227], v[18:21]
	v_mfma_f32_16x16x32_bf16 v[10:13], v[200:203], v[224:227], v[10:13]
	v_mfma_f32_16x16x32_bf16 v[2:5], v[200:203], v[232:235], v[2:5]
	v_mfma_f32_16x16x32_bf16 v[6:9], v[192:195], v[232:235], v[6:9]
	s_setprio 0
	s_barrier
	s_add_i32 s53, s53, 2
	s_add_u32 s20, s20, 0x100
	s_addc_u32 s21, s21, 0
	s_add_u32 s51, s51, 0x100
	s_addc_u32 s52, s52, 0
	s_cmp_gt_u32 s53, 9
	s_cbranch_scc0 .LBB0_263
	s_and_b64 vcc, exec, s[14:15]
	s_cbranch_vccz .LBB0_266
	s_barrier

.LBB0_291:
	ds_read_b128 v[154:157], v1
	ds_read_b128 v[158:161], v1 offset:1024
	ds_read_b128 v[162:165], v1 offset:2048
	ds_read_b128 v[166:169], v1 offset:3072
	ds_read_b128 v[170:173], v151
	ds_read_b128 v[174:177], v151 offset:1024
	ds_read_b128 v[178:181], v151 offset:2048
	ds_read_b128 v[182:185], v151 offset:3072
	s_add_u32 s30, s28, 0xfffe0080
	s_addc_u32 s31, s29, -1
	s_cmp_eq_u32 s64, 4
	s_cselect_b32 s35, s23, s31
	s_cselect_b32 s34, s60, s30
	s_cselect_b32 s31, s21, s63
	s_cselect_b32 s30, s61, s62
	v_lshl_add_u64 v[218:219], s[28:29], 0, v[140:141]
	s_add_i32 m0, s19, 0xc000
	ds_read_b128 v[186:189], v152
	ds_read_b128 v[190:193], v152 offset:1024
	ds_read_b128 v[194:197], v152 offset:2048
	ds_read_b128 v[198:201], v152 offset:3072
	ds_read_b128 v[202:205], v152 offset:4096
	ds_read_b128 v[206:209], v152 offset:5120
	ds_read_b128 v[210:213], v152 offset:6144
	ds_read_b128 v[214:217], v152 offset:7168
	global_load_lds_dwordx4 v[218:219], off
	v_lshl_add_u64 v[218:219], s[28:29], 0, v[142:143]
	s_add_i32 m0, s19, 0xe000
	s_nop 0
	global_load_lds_dwordx4 v[218:219], off
	s_waitcnt vmcnt(8)
	s_waitcnt lgkmcnt(0)
	s_barrier
	s_setprio 1
	s_waitcnt lgkmcnt(0)
	v_mfma_f32_16x16x32_bf16 v[126:129], v[154:157], v[186:189], v[126:129]
	v_mfma_f32_16x16x32_bf16 v[122:125], v[162:165], v[186:189], v[122:125]
	v_mfma_f32_16x16x32_bf16 v[114:117], v[162:165], v[194:197], v[114:117]
	v_mfma_f32_16x16x32_bf16 v[118:121], v[154:157], v[194:197], v[118:121]
	v_mfma_f32_16x16x32_bf16 v[102:105], v[154:157], v[202:205], v[102:105]
	v_mfma_f32_16x16x32_bf16 v[98:101], v[162:165], v[202:205], v[98:101]
	v_mfma_f32_16x16x32_bf16 v[82:85], v[162:165], v[210:213], v[82:85]
	v_mfma_f32_16x16x32_bf16 v[86:89], v[154:157], v[210:213], v[86:89]
	v_mfma_f32_16x16x32_bf16 v[126:129], v[158:161], v[190:193], v[126:129]
	v_mfma_f32_16x16x32_bf16 v[122:125], v[166:169], v[190:193], v[122:125]
	v_mfma_f32_16x16x32_bf16 v[114:117], v[166:169], v[198:201], v[114:117]
	v_mfma_f32_16x16x32_bf16 v[118:121], v[158:161], v[198:201], v[118:121]
	v_mfma_f32_16x16x32_bf16 v[102:105], v[158:161], v[206:209], v[102:105]
	v_mfma_f32_16x16x32_bf16 v[98:101], v[166:169], v[206:209], v[98:101]
	v_mfma_f32_16x16x32_bf16 v[82:85], v[166:169], v[214:217], v[82:85]
	v_mfma_f32_16x16x32_bf16 v[86:89], v[158:161], v[214:217], v[86:89]
	s_setprio 0
	s_setprio 1
	v_mfma_f32_16x16x32_bf16 v[110:113], v[170:173], v[186:189], v[110:113]
	v_mfma_f32_16x16x32_bf16 v[106:109], v[178:181], v[186:189], v[106:109]
	v_mfma_f32_16x16x32_bf16 v[90:93], v[178:181], v[194:197], v[90:93]
	v_mfma_f32_16x16x32_bf16 v[94:97], v[170:173], v[194:197], v[94:97]
	v_mfma_f32_16x16x32_bf16 v[78:81], v[170:173], v[202:205], v[78:81]
	v_mfma_f32_16x16x32_bf16 v[74:77], v[178:181], v[202:205], v[74:77]
	v_mfma_f32_16x16x32_bf16 v[66:69], v[178:181], v[210:213], v[66:69]
	v_mfma_f32_16x16x32_bf16 v[70:73], v[170:173], v[210:213], v[70:73]
	v_mfma_f32_16x16x32_bf16 v[110:113], v[174:177], v[190:193], v[110:113]
	v_mfma_f32_16x16x32_bf16 v[106:109], v[182:185], v[190:193], v[106:109]
	v_mfma_f32_16x16x32_bf16 v[90:93], v[182:185], v[198:201], v[90:93]
	v_mfma_f32_16x16x32_bf16 v[94:97], v[174:177], v[198:201], v[94:97]
	v_mfma_f32_16x16x32_bf16 v[78:81], v[174:177], v[206:209], v[78:81]
	v_mfma_f32_16x16x32_bf16 v[74:77], v[182:185], v[206:209], v[74:77]
	v_mfma_f32_16x16x32_bf16 v[66:69], v[182:185], v[214:217], v[66:69]
	v_mfma_f32_16x16x32_bf16 v[70:73], v[174:177], v[214:217], v[70:73]
	s_setprio 0
	s_barrier
	s_add_i32 s65, s53, s40
	v_lshl_add_u64 v[218:219], s[30:31], 0, v[134:135]
	s_mov_b32 m0, s65
	ds_read_b128 v[186:189], v152 offset:16384
	ds_read_b128 v[190:193], v152 offset:17408
	ds_read_b128 v[194:197], v152 offset:18432
	ds_read_b128 v[198:201], v152 offset:19456
	ds_read_b128 v[202:205], v152 offset:20480
	ds_read_b128 v[206:209], v152 offset:21504
	ds_read_b128 v[210:213], v152 offset:22528
	ds_read_b128 v[214:217], v152 offset:23552
	global_load_lds_dwordx4 v[218:219], off
	s_add_i32 m0, s65, 0x2000
	s_add_u32 s66, s30, 0x20000
	v_lshl_add_u64 v[220:221], s[30:31], 0, v[138:139]
	s_addc_u32 s67, s31, 0
	s_add_i32 s65, s54, s40
	global_load_lds_dwordx4 v[220:221], off
	v_lshl_add_u64 v[222:223], s[66:67], 0, v[134:135]
	s_mov_b32 m0, s65
	v_lshl_add_u64 v[224:225], s[34:35], 0, v[136:137]
	global_load_lds_dwordx4 v[222:223], off
	v_lshl_add_u64 v[222:223], s[66:67], 0, v[138:139]
	s_add_i32 m0, s65, 0x2000
	s_nop 0
	global_load_lds_dwordx4 v[222:223], off
	v_lshl_add_u64 v[222:223], s[34:35], 0, v[132:133]
	s_mov_b32 m0, s19
	s_nop 0
	global_load_lds_dwordx4 v[222:223], off
	s_mov_b32 m0, s41
	s_nop 0
	global_load_lds_dwordx4 v[224:225], off
	s_waitcnt vmcnt(8)
	s_waitcnt lgkmcnt(0)
	s_barrier
	s_setprio 1
	s_waitcnt lgkmcnt(0)
	v_mfma_f32_16x16x32_bf16 v[62:65], v[154:157], v[186:189], v[62:65]
	v_mfma_f32_16x16x32_bf16 v[58:61], v[162:165], v[186:189], v[58:61]
	v_mfma_f32_16x16x32_bf16 v[50:53], v[162:165], v[194:197], v[50:53]
	v_mfma_f32_16x16x32_bf16 v[54:57], v[154:157], v[194:197], v[54:57]
	v_mfma_f32_16x16x32_bf16 v[38:41], v[154:157], v[202:205], v[38:41]
	v_mfma_f32_16x16x32_bf16 v[34:37], v[162:165], v[202:205], v[34:37]
	v_mfma_f32_16x16x32_bf16 v[18:21], v[162:165], v[210:213], v[18:21]
	v_mfma_f32_16x16x32_bf16 v[22:25], v[154:157], v[210:213], v[22:25]
	v_mfma_f32_16x16x32_bf16 v[62:65], v[158:161], v[190:193], v[62:65]
	v_mfma_f32_16x16x32_bf16 v[58:61], v[166:169], v[190:193], v[58:61]
	v_mfma_f32_16x16x32_bf16 v[50:53], v[166:169], v[198:201], v[50:53]
	v_mfma_f32_16x16x32_bf16 v[54:57], v[158:161], v[198:201], v[54:57]
	v_mfma_f32_16x16x32_bf16 v[38:41], v[158:161], v[206:209], v[38:41]
	v_mfma_f32_16x16x32_bf16 v[34:37], v[166:169], v[206:209], v[34:37]
	v_mfma_f32_16x16x32_bf16 v[18:21], v[166:169], v[214:217], v[18:21]
	v_mfma_f32_16x16x32_bf16 v[22:25], v[158:161], v[214:217], v[22:25]
	s_setprio 0
	s_setprio 1
	v_mfma_f32_16x16x32_bf16 v[46:49], v[170:173], v[186:189], v[46:49]
	v_mfma_f32_16x16x32_bf16 v[42:45], v[178:181], v[186:189], v[42:45]
	v_mfma_f32_16x16x32_bf16 v[26:29], v[178:181], v[194:197], v[26:29]
	v_mfma_f32_16x16x32_bf16 v[30:33], v[170:173], v[194:197], v[30:33]
	v_mfma_f32_16x16x32_bf16 v[14:17], v[170:173], v[202:205], v[14:17]
	v_mfma_f32_16x16x32_bf16 v[10:13], v[178:181], v[202:205], v[10:13]
	v_mfma_f32_16x16x32_bf16 v[2:5], v[178:181], v[210:213], v[2:5]
	v_mfma_f32_16x16x32_bf16 v[6:9], v[170:173], v[210:213], v[6:9]
	v_mfma_f32_16x16x32_bf16 v[46:49], v[174:177], v[190:193], v[46:49]
	v_mfma_f32_16x16x32_bf16 v[42:45], v[182:185], v[190:193], v[42:45]
	v_mfma_f32_16x16x32_bf16 v[26:29], v[182:185], v[198:201], v[26:29]
	v_mfma_f32_16x16x32_bf16 v[30:33], v[174:177], v[198:201], v[30:33]
	v_mfma_f32_16x16x32_bf16 v[14:17], v[174:177], v[206:209], v[14:17]
	v_mfma_f32_16x16x32_bf16 v[10:13], v[182:185], v[206:209], v[10:13]
	v_mfma_f32_16x16x32_bf16 v[2:5], v[182:185], v[214:217], v[2:5]
	v_mfma_f32_16x16x32_bf16 v[6:9], v[174:177], v[214:217], v[6:9]
	s_setprio 0
	s_barrier
	s_add_i32 s65, 0, 0x18000
	v_add_u32_e32 v130, s65, v149
	s_add_i32 s66, 0, 0x1c000
	ds_read_b128 v[154:157], v130
	ds_read_b128 v[158:161], v130 offset:1024
	ds_read_b128 v[162:165], v130 offset:2048
	ds_read_b128 v[166:169], v130 offset:3072
	v_add_u32_e32 v130, s66, v149
	ds_read_b128 v[170:173], v130
	ds_read_b128 v[174:177], v130 offset:1024
	ds_read_b128 v[178:181], v130 offset:2048
	ds_read_b128 v[182:185], v130 offset:3072
	s_add_u32 s34, s34, 0x20000
	s_addc_u32 s35, s35, 0
	s_mov_b32 m0, s42
	v_lshl_add_u64 v[226:227], s[34:35], 0, v[132:133]
	ds_read_b128 v[186:189], v152 offset:32768
	ds_read_b128 v[190:193], v152 offset:33792
	ds_read_b128 v[194:197], v152 offset:34816
	ds_read_b128 v[198:201], v152 offset:35840
	ds_read_b128 v[202:205], v152 offset:36864
	ds_read_b128 v[206:209], v152 offset:37888
	ds_read_b128 v[210:213], v152 offset:38912
	ds_read_b128 v[214:217], v152 offset:39936
	global_load_lds_dwordx4 v[226:227], off
	v_lshl_add_u64 v[226:227], s[34:35], 0, v[136:137]
	s_mov_b32 m0, s43
	s_nop 0
	global_load_lds_dwordx4 v[226:227], off
	s_waitcnt vmcnt(8)
	s_waitcnt lgkmcnt(0)
	s_barrier
	s_setprio 1
	s_waitcnt lgkmcnt(0)
	v_mfma_f32_16x16x32_bf16 v[126:129], v[154:157], v[186:189], v[126:129]
	v_mfma_f32_16x16x32_bf16 v[122:125], v[162:165], v[186:189], v[122:125]
	v_mfma_f32_16x16x32_bf16 v[114:117], v[162:165], v[194:197], v[114:117]
	v_mfma_f32_16x16x32_bf16 v[118:121], v[154:157], v[194:197], v[118:121]
	v_mfma_f32_16x16x32_bf16 v[102:105], v[154:157], v[202:205], v[102:105]
	v_mfma_f32_16x16x32_bf16 v[98:101], v[162:165], v[202:205], v[98:101]
	v_mfma_f32_16x16x32_bf16 v[82:85], v[162:165], v[210:213], v[82:85]
	v_mfma_f32_16x16x32_bf16 v[86:89], v[154:157], v[210:213], v[86:89]
	v_mfma_f32_16x16x32_bf16 v[126:129], v[158:161], v[190:193], v[126:129]
	v_mfma_f32_16x16x32_bf16 v[122:125], v[166:169], v[190:193], v[122:125]
	v_mfma_f32_16x16x32_bf16 v[114:117], v[166:169], v[198:201], v[114:117]
	v_mfma_f32_16x16x32_bf16 v[118:121], v[158:161], v[198:201], v[118:121]
	v_mfma_f32_16x16x32_bf16 v[102:105], v[158:161], v[206:209], v[102:105]
	v_mfma_f32_16x16x32_bf16 v[98:101], v[166:169], v[206:209], v[98:101]
	v_mfma_f32_16x16x32_bf16 v[82:85], v[166:169], v[214:217], v[82:85]
	v_mfma_f32_16x16x32_bf16 v[86:89], v[158:161], v[214:217], v[86:89]
	s_setprio 0
	s_setprio 1
	v_mfma_f32_16x16x32_bf16 v[110:113], v[170:173], v[186:189], v[110:113]
	v_mfma_f32_16x16x32_bf16 v[106:109], v[178:181], v[186:189], v[106:109]
	v_mfma_f32_16x16x32_bf16 v[90:93], v[178:181], v[194:197], v[90:93]
	v_mfma_f32_16x16x32_bf16 v[94:97], v[170:173], v[194:197], v[94:97]
	v_mfma_f32_16x16x32_bf16 v[78:81], v[170:173], v[202:205], v[78:81]
	v_mfma_f32_16x16x32_bf16 v[74:77], v[178:181], v[202:205], v[74:77]
	v_mfma_f32_16x16x32_bf16 v[66:69], v[178:181], v[210:213], v[66:69]
	v_mfma_f32_16x16x32_bf16 v[70:73], v[170:173], v[210:213], v[70:73]
	v_mfma_f32_16x16x32_bf16 v[110:113], v[174:177], v[190:193], v[110:113]
	v_mfma_f32_16x16x32_bf16 v[106:109], v[182:185], v[190:193], v[106:109]
	v_mfma_f32_16x16x32_bf16 v[90:93], v[182:185], v[198:201], v[90:93]
	v_mfma_f32_16x16x32_bf16 v[94:97], v[174:177], v[198:201], v[94:97]
	v_mfma_f32_16x16x32_bf16 v[78:81], v[174:177], v[206:209], v[78:81]
	v_mfma_f32_16x16x32_bf16 v[74:77], v[182:185], v[206:209], v[74:77]
	v_mfma_f32_16x16x32_bf16 v[66:69], v[182:185], v[214:217], v[66:69]
	v_mfma_f32_16x16x32_bf16 v[70:73], v[174:177], v[214:217], v[70:73]
	s_setprio 0
	s_barrier
	s_add_i32 s34, s65, s40
	v_lshl_add_u64 v[218:219], v[218:219], 0, s[6:7]
	s_mov_b32 m0, s34
	ds_read_b128 v[186:189], v152 offset:49152
	ds_read_b128 v[190:193], v152 offset:50176
	ds_read_b128 v[194:197], v152 offset:51200
	ds_read_b128 v[198:201], v152 offset:52224
	ds_read_b128 v[202:205], v152 offset:53248
	ds_read_b128 v[206:209], v152 offset:54272
	ds_read_b128 v[210:213], v152 offset:55296
	ds_read_b128 v[214:217], v152 offset:56320
	global_load_lds_dwordx4 v[218:219], off
	s_add_i32 m0, s34, 0x2000
	s_add_u32 s30, s30, 0x20080
	v_lshl_add_u64 v[218:219], v[220:221], 0, s[6:7]
	s_addc_u32 s31, s31, 0
	s_add_i32 s34, s66, s40
	global_load_lds_dwordx4 v[218:219], off
	v_lshl_add_u64 v[218:219], s[30:31], 0, v[134:135]
	s_mov_b32 m0, s34
	s_nop 0
	global_load_lds_dwordx4 v[218:219], off
	v_lshl_add_u64 v[218:219], s[30:31], 0, v[138:139]
	s_add_i32 m0, s34, 0x2000
	s_nop 0
	global_load_lds_dwordx4 v[218:219], off
	v_lshl_add_u64 v[218:219], v[222:223], 0, s[6:7]
	s_mov_b32 m0, s49
	s_nop 0
	global_load_lds_dwordx4 v[218:219], off
	v_lshl_add_u64 v[218:219], v[224:225], 0, s[6:7]
	s_mov_b32 m0, s50
	s_nop 0
	global_load_lds_dwordx4 v[218:219], off
	s_waitcnt vmcnt(8)
	s_waitcnt lgkmcnt(0)
	s_barrier
	s_setprio 1
	s_waitcnt lgkmcnt(0)
	v_mfma_f32_16x16x32_bf16 v[62:65], v[154:157], v[186:189], v[62:65]
	v_mfma_f32_16x16x32_bf16 v[58:61], v[162:165], v[186:189], v[58:61]
	v_mfma_f32_16x16x32_bf16 v[50:53], v[162:165], v[194:197], v[50:53]
	v_mfma_f32_16x16x32_bf16 v[54:57], v[154:157], v[194:197], v[54:57]
	v_mfma_f32_16x16x32_bf16 v[38:41], v[154:157], v[202:205], v[38:41]
	v_mfma_f32_16x16x32_bf16 v[34:37], v[162:165], v[202:205], v[34:37]
	v_mfma_f32_16x16x32_bf16 v[18:21], v[162:165], v[210:213], v[18:21]
	v_mfma_f32_16x16x32_bf16 v[22:25], v[154:157], v[210:213], v[22:25]
	v_mfma_f32_16x16x32_bf16 v[62:65], v[158:161], v[190:193], v[62:65]
	v_mfma_f32_16x16x32_bf16 v[58:61], v[166:169], v[190:193], v[58:61]
	v_mfma_f32_16x16x32_bf16 v[50:53], v[166:169], v[198:201], v[50:53]
	v_mfma_f32_16x16x32_bf16 v[54:57], v[158:161], v[198:201], v[54:57]
	v_mfma_f32_16x16x32_bf16 v[38:41], v[158:161], v[206:209], v[38:41]
	v_mfma_f32_16x16x32_bf16 v[34:37], v[166:169], v[206:209], v[34:37]
	v_mfma_f32_16x16x32_bf16 v[18:21], v[166:169], v[214:217], v[18:21]
	v_mfma_f32_16x16x32_bf16 v[22:25], v[158:161], v[214:217], v[22:25]
	s_setprio 0
	s_setprio 1
	v_mfma_f32_16x16x32_bf16 v[46:49], v[170:173], v[186:189], v[46:49]
	v_mfma_f32_16x16x32_bf16 v[42:45], v[178:181], v[186:189], v[42:45]
	v_mfma_f32_16x16x32_bf16 v[26:29], v[178:181], v[194:197], v[26:29]
	v_mfma_f32_16x16x32_bf16 v[30:33], v[170:173], v[194:197], v[30:33]
	v_mfma_f32_16x16x32_bf16 v[14:17], v[170:173], v[202:205], v[14:17]
	v_mfma_f32_16x16x32_bf16 v[10:13], v[178:181], v[202:205], v[10:13]
	v_mfma_f32_16x16x32_bf16 v[2:5], v[178:181], v[210:213], v[2:5]
	v_mfma_f32_16x16x32_bf16 v[6:9], v[170:173], v[210:213], v[6:9]
	v_mfma_f32_16x16x32_bf16 v[46:49], v[174:177], v[190:193], v[46:49]
	v_mfma_f32_16x16x32_bf16 v[42:45], v[182:185], v[190:193], v[42:45]
	v_mfma_f32_16x16x32_bf16 v[26:29], v[182:185], v[198:201], v[26:29]
	v_mfma_f32_16x16x32_bf16 v[30:33], v[174:177], v[198:201], v[30:33]
	v_mfma_f32_16x16x32_bf16 v[14:17], v[174:177], v[206:209], v[14:17]
	v_mfma_f32_16x16x32_bf16 v[10:13], v[182:185], v[206:209], v[10:13]
	v_mfma_f32_16x16x32_bf16 v[2:5], v[182:185], v[214:217], v[2:5]
	v_mfma_f32_16x16x32_bf16 v[6:9], v[174:177], v[214:217], v[6:9]
	s_setprio 0
	s_barrier
	s_add_i32 s64, s64, 2
	s_add_u32 s28, s28, 0x100
	s_addc_u32 s29, s29, 0
	s_add_u32 s62, s62, 0x100
	s_addc_u32 s63, s63, 0
	s_cmp_gt_u32 s64, 5
	s_cbranch_scc0 .LBB0_291
	s_and_b64 vcc, exec, s[8:9]
	s_cbranch_vccz .LBB0_294
	s_barrier

.LBB0_531:
	ds_read_b128 v[146:149], v152
	ds_read_b128 v[156:159], v152 offset:1024
	ds_read_b128 v[160:163], v152 offset:2048
	ds_read_b128 v[164:167], v152 offset:3072
	ds_read_b128 v[168:171], v153
	ds_read_b128 v[172:175], v153 offset:1024
	ds_read_b128 v[176:179], v153 offset:2048
	ds_read_b128 v[180:183], v153 offset:3072
	s_add_u32 s22, s20, 0xfffc0080
	s_addc_u32 s23, s21, -1
	s_cmp_eq_u32 s46, 12
	s_cselect_b32 s25, s13, s23
	s_cselect_b32 s24, s42, s22
	s_cselect_b32 s23, s11, s45
	s_cselect_b32 s22, s43, s44
	v_lshl_add_u64 v[216:217], s[20:21], 0, v[138:139]
	s_add_i32 m0, s19, 0xc000
	ds_read_b128 v[184:187], v154
	ds_read_b128 v[188:191], v154 offset:1024
	ds_read_b128 v[192:195], v154 offset:2048
	ds_read_b128 v[196:199], v154 offset:3072
	ds_read_b128 v[200:203], v154 offset:4096
	ds_read_b128 v[204:207], v154 offset:5120
	ds_read_b128 v[208:211], v154 offset:6144
	ds_read_b128 v[212:215], v154 offset:7168
	global_load_lds_dwordx4 v[216:217], off
	v_lshl_add_u64 v[216:217], s[20:21], 0, v[140:141]
	s_add_i32 m0, s19, 0xe000
	s_nop 0
	global_load_lds_dwordx4 v[216:217], off
	s_waitcnt vmcnt(8)
	s_waitcnt lgkmcnt(0)
	s_barrier
	s_setprio 1
	s_waitcnt lgkmcnt(0)
	v_mfma_f32_16x16x32_bf16 v[126:129], v[146:149], v[184:187], v[126:129]
	v_mfma_f32_16x16x32_bf16 v[122:125], v[160:163], v[184:187], v[122:125]
	v_mfma_f32_16x16x32_bf16 v[106:109], v[160:163], v[192:195], v[106:109]
	v_mfma_f32_16x16x32_bf16 v[110:113], v[146:149], v[192:195], v[110:113]
	v_mfma_f32_16x16x32_bf16 v[94:97], v[146:149], v[200:203], v[94:97]
	v_mfma_f32_16x16x32_bf16 v[90:93], v[160:163], v[200:203], v[90:93]
	v_mfma_f32_16x16x32_bf16 v[74:77], v[160:163], v[208:211], v[74:77]
	v_mfma_f32_16x16x32_bf16 v[78:81], v[146:149], v[208:211], v[78:81]
	v_mfma_f32_16x16x32_bf16 v[126:129], v[156:159], v[188:191], v[126:129]
	v_mfma_f32_16x16x32_bf16 v[122:125], v[164:167], v[188:191], v[122:125]
	v_mfma_f32_16x16x32_bf16 v[106:109], v[164:167], v[196:199], v[106:109]
	v_mfma_f32_16x16x32_bf16 v[110:113], v[156:159], v[196:199], v[110:113]
	v_mfma_f32_16x16x32_bf16 v[94:97], v[156:159], v[204:207], v[94:97]
	v_mfma_f32_16x16x32_bf16 v[90:93], v[164:167], v[204:207], v[90:93]
	v_mfma_f32_16x16x32_bf16 v[74:77], v[164:167], v[212:215], v[74:77]
	v_mfma_f32_16x16x32_bf16 v[78:81], v[156:159], v[212:215], v[78:81]
	s_setprio 0
	s_setprio 1
	v_mfma_f32_16x16x32_bf16 v[118:121], v[168:171], v[184:187], v[118:121]
	v_mfma_f32_16x16x32_bf16 v[114:117], v[176:179], v[184:187], v[114:117]
	v_mfma_f32_16x16x32_bf16 v[98:101], v[176:179], v[192:195], v[98:101]
	v_mfma_f32_16x16x32_bf16 v[102:105], v[168:171], v[192:195], v[102:105]
	v_mfma_f32_16x16x32_bf16 v[86:89], v[168:171], v[200:203], v[86:89]
	v_mfma_f32_16x16x32_bf16 v[82:85], v[176:179], v[200:203], v[82:85]
	v_mfma_f32_16x16x32_bf16 v[66:69], v[176:179], v[208:211], v[66:69]
	v_mfma_f32_16x16x32_bf16 v[70:73], v[168:171], v[208:211], v[70:73]
	v_mfma_f32_16x16x32_bf16 v[118:121], v[172:175], v[188:191], v[118:121]
	v_mfma_f32_16x16x32_bf16 v[114:117], v[180:183], v[188:191], v[114:117]
	v_mfma_f32_16x16x32_bf16 v[98:101], v[180:183], v[196:199], v[98:101]
	v_mfma_f32_16x16x32_bf16 v[102:105], v[172:175], v[196:199], v[102:105]
	v_mfma_f32_16x16x32_bf16 v[86:89], v[172:175], v[204:207], v[86:89]
	v_mfma_f32_16x16x32_bf16 v[82:85], v[180:183], v[204:207], v[82:85]
	v_mfma_f32_16x16x32_bf16 v[66:69], v[180:183], v[212:215], v[66:69]
	v_mfma_f32_16x16x32_bf16 v[70:73], v[172:175], v[212:215], v[70:73]
	s_setprio 0
	s_barrier
	s_add_i32 s47, s39, s29
	v_lshl_add_u64 v[216:217], s[22:23], 0, v[132:133]
	s_mov_b32 m0, s47
	ds_read_b128 v[184:187], v154 offset:16384
	ds_read_b128 v[188:191], v154 offset:17408
	ds_read_b128 v[192:195], v154 offset:18432
	ds_read_b128 v[196:199], v154 offset:19456
	ds_read_b128 v[200:203], v154 offset:20480
	ds_read_b128 v[204:207], v154 offset:21504
	ds_read_b128 v[208:211], v154 offset:22528
	ds_read_b128 v[212:215], v154 offset:23552
	global_load_lds_dwordx4 v[216:217], off
	s_add_i32 m0, s47, 0x2000
	s_add_u32 s48, s22, 0x40000
	v_lshl_add_u64 v[218:219], s[22:23], 0, v[136:137]
	s_addc_u32 s49, s23, 0
	s_add_i32 s47, s40, s29
	global_load_lds_dwordx4 v[218:219], off
	v_lshl_add_u64 v[220:221], s[48:49], 0, v[132:133]
	s_mov_b32 m0, s47
	v_lshl_add_u64 v[222:223], s[24:25], 0, v[134:135]
	global_load_lds_dwordx4 v[220:221], off
	v_lshl_add_u64 v[220:221], s[48:49], 0, v[136:137]
	s_add_i32 m0, s47, 0x2000
	s_nop 0
	global_load_lds_dwordx4 v[220:221], off
	v_lshl_add_u64 v[220:221], s[24:25], 0, v[130:131]
	s_mov_b32 m0, s19
	s_nop 0
	global_load_lds_dwordx4 v[220:221], off
	s_mov_b32 m0, s30
	s_nop 0
	global_load_lds_dwordx4 v[222:223], off
	s_waitcnt vmcnt(8)
	s_waitcnt lgkmcnt(0)
	s_barrier
	s_setprio 1
	s_waitcnt lgkmcnt(0)
	v_mfma_f32_16x16x32_bf16 v[62:65], v[146:149], v[184:187], v[62:65]
	v_mfma_f32_16x16x32_bf16 v[58:61], v[160:163], v[184:187], v[58:61]
	v_mfma_f32_16x16x32_bf16 v[42:45], v[160:163], v[192:195], v[42:45]
	v_mfma_f32_16x16x32_bf16 v[46:49], v[146:149], v[192:195], v[46:49]
	v_mfma_f32_16x16x32_bf16 v[30:33], v[146:149], v[200:203], v[30:33]
	v_mfma_f32_16x16x32_bf16 v[26:29], v[160:163], v[200:203], v[26:29]
	v_mfma_f32_16x16x32_bf16 v[10:13], v[160:163], v[208:211], v[10:13]
	v_mfma_f32_16x16x32_bf16 v[14:17], v[146:149], v[208:211], v[14:17]
	v_mfma_f32_16x16x32_bf16 v[62:65], v[156:159], v[188:191], v[62:65]
	v_mfma_f32_16x16x32_bf16 v[58:61], v[164:167], v[188:191], v[58:61]
	v_mfma_f32_16x16x32_bf16 v[42:45], v[164:167], v[196:199], v[42:45]
	v_mfma_f32_16x16x32_bf16 v[46:49], v[156:159], v[196:199], v[46:49]
	v_mfma_f32_16x16x32_bf16 v[30:33], v[156:159], v[204:207], v[30:33]
	v_mfma_f32_16x16x32_bf16 v[26:29], v[164:167], v[204:207], v[26:29]
	v_mfma_f32_16x16x32_bf16 v[10:13], v[164:167], v[212:215], v[10:13]
	v_mfma_f32_16x16x32_bf16 v[14:17], v[156:159], v[212:215], v[14:17]
	s_setprio 0
	s_setprio 1
	v_mfma_f32_16x16x32_bf16 v[54:57], v[168:171], v[184:187], v[54:57]
	v_mfma_f32_16x16x32_bf16 v[50:53], v[176:179], v[184:187], v[50:53]
	v_mfma_f32_16x16x32_bf16 v[34:37], v[176:179], v[192:195], v[34:37]
	v_mfma_f32_16x16x32_bf16 v[38:41], v[168:171], v[192:195], v[38:41]
	v_mfma_f32_16x16x32_bf16 v[22:25], v[168:171], v[200:203], v[22:25]
	v_mfma_f32_16x16x32_bf16 v[18:21], v[176:179], v[200:203], v[18:21]
	v_mfma_f32_16x16x32_bf16 v[2:5], v[176:179], v[208:211], v[2:5]
	v_mfma_f32_16x16x32_bf16 v[6:9], v[168:171], v[208:211], v[6:9]
	v_mfma_f32_16x16x32_bf16 v[54:57], v[172:175], v[188:191], v[54:57]
	v_mfma_f32_16x16x32_bf16 v[50:53], v[180:183], v[188:191], v[50:53]
	v_mfma_f32_16x16x32_bf16 v[34:37], v[180:183], v[196:199], v[34:37]
	v_mfma_f32_16x16x32_bf16 v[38:41], v[172:175], v[196:199], v[38:41]
	v_mfma_f32_16x16x32_bf16 v[22:25], v[172:175], v[204:207], v[22:25]
	v_mfma_f32_16x16x32_bf16 v[18:21], v[180:183], v[204:207], v[18:21]
	v_mfma_f32_16x16x32_bf16 v[2:5], v[180:183], v[212:215], v[2:5]
	v_mfma_f32_16x16x32_bf16 v[6:9], v[172:175], v[212:215], v[6:9]
	s_setprio 0
	s_barrier
	s_add_i32 s47, 0, 0x18000
	v_add_u32_e32 v155, s47, v150
	s_add_i32 s48, 0, 0x1c000
	ds_read_b128 v[146:149], v155
	ds_read_b128 v[156:159], v155 offset:1024
	ds_read_b128 v[160:163], v155 offset:2048
	ds_read_b128 v[164:167], v155 offset:3072
	v_add_u32_e32 v155, s48, v150
	ds_read_b128 v[168:171], v155
	ds_read_b128 v[172:175], v155 offset:1024
	ds_read_b128 v[176:179], v155 offset:2048
	ds_read_b128 v[180:183], v155 offset:3072
	s_add_u32 s24, s24, 0x40000
	s_addc_u32 s25, s25, 0
	s_mov_b32 m0, s31
	v_lshl_add_u64 v[224:225], s[24:25], 0, v[130:131]
	ds_read_b128 v[184:187], v154 offset:32768
	ds_read_b128 v[188:191], v154 offset:33792
	ds_read_b128 v[192:195], v154 offset:34816
	ds_read_b128 v[196:199], v154 offset:35840
	ds_read_b128 v[200:203], v154 offset:36864
	ds_read_b128 v[204:207], v154 offset:37888
	ds_read_b128 v[208:211], v154 offset:38912
	ds_read_b128 v[212:215], v154 offset:39936
	global_load_lds_dwordx4 v[224:225], off
	v_lshl_add_u64 v[224:225], s[24:25], 0, v[134:135]
	s_mov_b32 m0, s33
	s_nop 0
	global_load_lds_dwordx4 v[224:225], off
	s_waitcnt vmcnt(8)
	s_waitcnt lgkmcnt(0)
	s_barrier
	s_setprio 1
	s_waitcnt lgkmcnt(0)
	v_mfma_f32_16x16x32_bf16 v[126:129], v[146:149], v[184:187], v[126:129]
	v_mfma_f32_16x16x32_bf16 v[122:125], v[160:163], v[184:187], v[122:125]
	v_mfma_f32_16x16x32_bf16 v[106:109], v[160:163], v[192:195], v[106:109]
	v_mfma_f32_16x16x32_bf16 v[110:113], v[146:149], v[192:195], v[110:113]
	v_mfma_f32_16x16x32_bf16 v[94:97], v[146:149], v[200:203], v[94:97]
	v_mfma_f32_16x16x32_bf16 v[90:93], v[160:163], v[200:203], v[90:93]
	v_mfma_f32_16x16x32_bf16 v[74:77], v[160:163], v[208:211], v[74:77]
	v_mfma_f32_16x16x32_bf16 v[78:81], v[146:149], v[208:211], v[78:81]
	v_mfma_f32_16x16x32_bf16 v[126:129], v[156:159], v[188:191], v[126:129]
	v_mfma_f32_16x16x32_bf16 v[122:125], v[164:167], v[188:191], v[122:125]
	v_mfma_f32_16x16x32_bf16 v[106:109], v[164:167], v[196:199], v[106:109]
	v_mfma_f32_16x16x32_bf16 v[110:113], v[156:159], v[196:199], v[110:113]
	v_mfma_f32_16x16x32_bf16 v[94:97], v[156:159], v[204:207], v[94:97]
	v_mfma_f32_16x16x32_bf16 v[90:93], v[164:167], v[204:207], v[90:93]
	v_mfma_f32_16x16x32_bf16 v[74:77], v[164:167], v[212:215], v[74:77]
	v_mfma_f32_16x16x32_bf16 v[78:81], v[156:159], v[212:215], v[78:81]
	s_setprio 0
	s_setprio 1
	v_mfma_f32_16x16x32_bf16 v[118:121], v[168:171], v[184:187], v[118:121]
	v_mfma_f32_16x16x32_bf16 v[114:117], v[176:179], v[184:187], v[114:117]
	v_mfma_f32_16x16x32_bf16 v[98:101], v[176:179], v[192:195], v[98:101]
	v_mfma_f32_16x16x32_bf16 v[102:105], v[168:171], v[192:195], v[102:105]
	v_mfma_f32_16x16x32_bf16 v[86:89], v[168:171], v[200:203], v[86:89]
	v_mfma_f32_16x16x32_bf16 v[82:85], v[176:179], v[200:203], v[82:85]
	v_mfma_f32_16x16x32_bf16 v[66:69], v[176:179], v[208:211], v[66:69]
	v_mfma_f32_16x16x32_bf16 v[70:73], v[168:171], v[208:211], v[70:73]
	v_mfma_f32_16x16x32_bf16 v[118:121], v[172:175], v[188:191], v[118:121]
	v_mfma_f32_16x16x32_bf16 v[114:117], v[180:183], v[188:191], v[114:117]
	v_mfma_f32_16x16x32_bf16 v[98:101], v[180:183], v[196:199], v[98:101]
	v_mfma_f32_16x16x32_bf16 v[102:105], v[172:175], v[196:199], v[102:105]
	v_mfma_f32_16x16x32_bf16 v[86:89], v[172:175], v[204:207], v[86:89]
	v_mfma_f32_16x16x32_bf16 v[82:85], v[180:183], v[204:207], v[82:85]
	v_mfma_f32_16x16x32_bf16 v[66:69], v[180:183], v[212:215], v[66:69]
	v_mfma_f32_16x16x32_bf16 v[70:73], v[172:175], v[212:215], v[70:73]
	s_setprio 0
	s_barrier
	s_add_i32 s24, s47, s29
	v_lshl_add_u64 v[216:217], v[216:217], 0, s[6:7]
	s_mov_b32 m0, s24
	ds_read_b128 v[184:187], v154 offset:49152
	ds_read_b128 v[188:191], v154 offset:50176
	ds_read_b128 v[192:195], v154 offset:51200
	ds_read_b128 v[196:199], v154 offset:52224
	ds_read_b128 v[200:203], v154 offset:53248
	ds_read_b128 v[204:207], v154 offset:54272
	ds_read_b128 v[208:211], v154 offset:55296
	ds_read_b128 v[212:215], v154 offset:56320
	global_load_lds_dwordx4 v[216:217], off
	s_add_i32 m0, s24, 0x2000
	s_add_u32 s22, s22, 0x40080
	v_lshl_add_u64 v[216:217], v[218:219], 0, s[6:7]
	s_addc_u32 s23, s23, 0
	s_add_i32 s24, s48, s29
	global_load_lds_dwordx4 v[216:217], off
	v_lshl_add_u64 v[216:217], s[22:23], 0, v[132:133]
	s_mov_b32 m0, s24
	s_nop 0
	global_load_lds_dwordx4 v[216:217], off
	v_lshl_add_u64 v[216:217], s[22:23], 0, v[136:137]
	s_add_i32 m0, s24, 0x2000
	s_nop 0
	global_load_lds_dwordx4 v[216:217], off
	v_lshl_add_u64 v[216:217], v[220:221], 0, s[6:7]
	s_mov_b32 m0, s35
	s_nop 0
	global_load_lds_dwordx4 v[216:217], off
	v_lshl_add_u64 v[216:217], v[222:223], 0, s[6:7]
	s_mov_b32 m0, s36
	s_nop 0
	global_load_lds_dwordx4 v[216:217], off
	s_waitcnt vmcnt(8)
	s_waitcnt lgkmcnt(0)
	s_barrier
	s_setprio 1
	s_waitcnt lgkmcnt(0)
	v_mfma_f32_16x16x32_bf16 v[62:65], v[146:149], v[184:187], v[62:65]
	v_mfma_f32_16x16x32_bf16 v[58:61], v[160:163], v[184:187], v[58:61]
	v_mfma_f32_16x16x32_bf16 v[42:45], v[160:163], v[192:195], v[42:45]
	v_mfma_f32_16x16x32_bf16 v[46:49], v[146:149], v[192:195], v[46:49]
	v_mfma_f32_16x16x32_bf16 v[30:33], v[146:149], v[200:203], v[30:33]
	v_mfma_f32_16x16x32_bf16 v[26:29], v[160:163], v[200:203], v[26:29]
	v_mfma_f32_16x16x32_bf16 v[10:13], v[160:163], v[208:211], v[10:13]
	v_mfma_f32_16x16x32_bf16 v[14:17], v[146:149], v[208:211], v[14:17]
	v_mfma_f32_16x16x32_bf16 v[62:65], v[156:159], v[188:191], v[62:65]
	v_mfma_f32_16x16x32_bf16 v[58:61], v[164:167], v[188:191], v[58:61]
	v_mfma_f32_16x16x32_bf16 v[42:45], v[164:167], v[196:199], v[42:45]
	v_mfma_f32_16x16x32_bf16 v[46:49], v[156:159], v[196:199], v[46:49]
	v_mfma_f32_16x16x32_bf16 v[30:33], v[156:159], v[204:207], v[30:33]
	v_mfma_f32_16x16x32_bf16 v[26:29], v[164:167], v[204:207], v[26:29]
	v_mfma_f32_16x16x32_bf16 v[10:13], v[164:167], v[212:215], v[10:13]
	v_mfma_f32_16x16x32_bf16 v[14:17], v[156:159], v[212:215], v[14:17]
	s_setprio 0
	s_setprio 1
	v_mfma_f32_16x16x32_bf16 v[54:57], v[168:171], v[184:187], v[54:57]
	v_mfma_f32_16x16x32_bf16 v[50:53], v[176:179], v[184:187], v[50:53]
	v_mfma_f32_16x16x32_bf16 v[34:37], v[176:179], v[192:195], v[34:37]
	v_mfma_f32_16x16x32_bf16 v[38:41], v[168:171], v[192:195], v[38:41]
	v_mfma_f32_16x16x32_bf16 v[22:25], v[168:171], v[200:203], v[22:25]
	v_mfma_f32_16x16x32_bf16 v[18:21], v[176:179], v[200:203], v[18:21]
	v_mfma_f32_16x16x32_bf16 v[2:5], v[176:179], v[208:211], v[2:5]
	v_mfma_f32_16x16x32_bf16 v[6:9], v[168:171], v[208:211], v[6:9]
	v_mfma_f32_16x16x32_bf16 v[54:57], v[172:175], v[188:191], v[54:57]
	v_mfma_f32_16x16x32_bf16 v[50:53], v[180:183], v[188:191], v[50:53]
	v_mfma_f32_16x16x32_bf16 v[34:37], v[180:183], v[196:199], v[34:37]
	v_mfma_f32_16x16x32_bf16 v[38:41], v[172:175], v[196:199], v[38:41]
	v_mfma_f32_16x16x32_bf16 v[22:25], v[172:175], v[204:207], v[22:25]
	v_mfma_f32_16x16x32_bf16 v[18:21], v[180:183], v[204:207], v[18:21]
	v_mfma_f32_16x16x32_bf16 v[2:5], v[180:183], v[212:215], v[2:5]
	v_mfma_f32_16x16x32_bf16 v[6:9], v[172:175], v[212:215], v[6:9]
	s_setprio 0
	s_barrier
	s_add_i32 s46, s46, 2
	s_add_u32 s20, s20, 0x100
	s_addc_u32 s21, s21, 0
	s_add_u32 s44, s44, 0x100
	s_addc_u32 s45, s45, 0
	s_cmp_gt_u32 s46, 13
	s_cbranch_scc0 .LBB0_531
	s_and_b64 vcc, exec, s[8:9]
	v_readlane_b32 s42, v245, 12
	v_readlane_b32 s43, v245, 13
	s_cbranch_vccz .LBB0_534
	s_barrier

.LBB0_556:
	ds_read_b128 v[146:149], v154
	ds_read_b128 v[158:161], v154 offset:1024
	ds_read_b128 v[162:165], v154 offset:2048
	ds_read_b128 v[166:169], v154 offset:3072
	ds_read_b128 v[170:173], v155
	ds_read_b128 v[174:177], v155 offset:1024
	ds_read_b128 v[178:181], v155 offset:2048
	ds_read_b128 v[182:185], v155 offset:3072
	s_add_u32 s26, s24, 0xfffc0080
	s_addc_u32 s27, s25, -1
	s_cmp_eq_u32 s52, 12
	s_cselect_b32 s29, s17, s27
	s_cselect_b32 s28, s48, s26
	s_cselect_b32 s27, s15, s51
	s_cselect_b32 s26, s49, s50
	v_lshl_add_u64 v[150:151], s[24:25], 0, v[138:139]
	s_add_i32 m0, s23, 0xc000
	ds_read_b128 v[186:189], v156
	ds_read_b128 v[190:193], v156 offset:1024
	ds_read_b128 v[194:197], v156 offset:2048
	ds_read_b128 v[198:201], v156 offset:3072
	ds_read_b128 v[202:205], v156 offset:4096
	ds_read_b128 v[206:209], v156 offset:5120
	ds_read_b128 v[210:213], v156 offset:6144
	ds_read_b128 v[214:217], v156 offset:7168
	global_load_lds_dwordx4 v[150:151], off
	v_lshl_add_u64 v[150:151], s[24:25], 0, v[140:141]
	s_add_i32 m0, s23, 0xe000
	s_nop 0
	global_load_lds_dwordx4 v[150:151], off
	s_waitcnt vmcnt(8)
	s_waitcnt lgkmcnt(0)
	s_barrier
	s_setprio 1
	s_waitcnt lgkmcnt(0)
	v_mfma_f32_16x16x32_bf16 v[126:129], v[146:149], v[186:189], v[126:129]
	v_mfma_f32_16x16x32_bf16 v[122:125], v[162:165], v[186:189], v[122:125]
	v_mfma_f32_16x16x32_bf16 v[106:109], v[162:165], v[194:197], v[106:109]
	v_mfma_f32_16x16x32_bf16 v[110:113], v[146:149], v[194:197], v[110:113]
	v_mfma_f32_16x16x32_bf16 v[94:97], v[146:149], v[202:205], v[94:97]
	v_mfma_f32_16x16x32_bf16 v[90:93], v[162:165], v[202:205], v[90:93]
	v_mfma_f32_16x16x32_bf16 v[74:77], v[162:165], v[210:213], v[74:77]
	v_mfma_f32_16x16x32_bf16 v[78:81], v[146:149], v[210:213], v[78:81]
	v_mfma_f32_16x16x32_bf16 v[126:129], v[158:161], v[190:193], v[126:129]
	v_mfma_f32_16x16x32_bf16 v[122:125], v[166:169], v[190:193], v[122:125]
	v_mfma_f32_16x16x32_bf16 v[106:109], v[166:169], v[198:201], v[106:109]
	v_mfma_f32_16x16x32_bf16 v[110:113], v[158:161], v[198:201], v[110:113]
	v_mfma_f32_16x16x32_bf16 v[94:97], v[158:161], v[206:209], v[94:97]
	v_mfma_f32_16x16x32_bf16 v[90:93], v[166:169], v[206:209], v[90:93]
	v_mfma_f32_16x16x32_bf16 v[74:77], v[166:169], v[214:217], v[74:77]
	v_mfma_f32_16x16x32_bf16 v[78:81], v[158:161], v[214:217], v[78:81]
	s_setprio 0
	s_setprio 1
	v_mfma_f32_16x16x32_bf16 v[118:121], v[170:173], v[186:189], v[118:121]
	v_mfma_f32_16x16x32_bf16 v[114:117], v[178:181], v[186:189], v[114:117]
	v_mfma_f32_16x16x32_bf16 v[98:101], v[178:181], v[194:197], v[98:101]
	v_mfma_f32_16x16x32_bf16 v[102:105], v[170:173], v[194:197], v[102:105]
	v_mfma_f32_16x16x32_bf16 v[86:89], v[170:173], v[202:205], v[86:89]
	v_mfma_f32_16x16x32_bf16 v[82:85], v[178:181], v[202:205], v[82:85]
	v_mfma_f32_16x16x32_bf16 v[66:69], v[178:181], v[210:213], v[66:69]
	v_mfma_f32_16x16x32_bf16 v[70:73], v[170:173], v[210:213], v[70:73]
	v_mfma_f32_16x16x32_bf16 v[118:121], v[174:177], v[190:193], v[118:121]
	v_mfma_f32_16x16x32_bf16 v[114:117], v[182:185], v[190:193], v[114:117]
	v_mfma_f32_16x16x32_bf16 v[98:101], v[182:185], v[198:201], v[98:101]
	v_mfma_f32_16x16x32_bf16 v[102:105], v[174:177], v[198:201], v[102:105]
	v_mfma_f32_16x16x32_bf16 v[86:89], v[174:177], v[206:209], v[86:89]
	v_mfma_f32_16x16x32_bf16 v[82:85], v[182:185], v[206:209], v[82:85]
	v_mfma_f32_16x16x32_bf16 v[66:69], v[182:185], v[214:217], v[66:69]
	v_mfma_f32_16x16x32_bf16 v[70:73], v[174:177], v[214:217], v[70:73]
	s_setprio 0
	s_barrier
	s_add_i32 s53, s45, s36
	v_lshl_add_u64 v[150:151], s[26:27], 0, v[132:133]
	s_mov_b32 m0, s53
	ds_read_b128 v[186:189], v156 offset:16384
	ds_read_b128 v[190:193], v156 offset:17408
	ds_read_b128 v[194:197], v156 offset:18432
	ds_read_b128 v[198:201], v156 offset:19456
	ds_read_b128 v[202:205], v156 offset:20480
	ds_read_b128 v[206:209], v156 offset:21504
	ds_read_b128 v[210:213], v156 offset:22528
	ds_read_b128 v[214:217], v156 offset:23552
	global_load_lds_dwordx4 v[150:151], off
	s_add_i32 m0, s53, 0x2000
	s_add_u32 s54, s26, 0x40000
	v_lshl_add_u64 v[218:219], s[26:27], 0, v[136:137]
	s_addc_u32 s55, s27, 0
	s_add_i32 s53, s46, s36
	global_load_lds_dwordx4 v[218:219], off
	v_lshl_add_u64 v[220:221], s[54:55], 0, v[132:133]
	s_mov_b32 m0, s53
	v_lshl_add_u64 v[222:223], s[28:29], 0, v[134:135]
	global_load_lds_dwordx4 v[220:221], off
	v_lshl_add_u64 v[220:221], s[54:55], 0, v[136:137]
	s_add_i32 m0, s53, 0x2000
	s_nop 0
	global_load_lds_dwordx4 v[220:221], off
	v_lshl_add_u64 v[220:221], s[28:29], 0, v[130:131]
	s_mov_b32 m0, s23
	s_nop 0
	global_load_lds_dwordx4 v[220:221], off
	s_mov_b32 m0, s37
	s_nop 0
	global_load_lds_dwordx4 v[222:223], off
	s_waitcnt vmcnt(8)
	s_waitcnt lgkmcnt(0)
	s_barrier
	s_setprio 1
	s_waitcnt lgkmcnt(0)
	v_mfma_f32_16x16x32_bf16 v[62:65], v[146:149], v[186:189], v[62:65]
	v_mfma_f32_16x16x32_bf16 v[58:61], v[162:165], v[186:189], v[58:61]
	v_mfma_f32_16x16x32_bf16 v[42:45], v[162:165], v[194:197], v[42:45]
	v_mfma_f32_16x16x32_bf16 v[46:49], v[146:149], v[194:197], v[46:49]
	v_mfma_f32_16x16x32_bf16 v[30:33], v[146:149], v[202:205], v[30:33]
	v_mfma_f32_16x16x32_bf16 v[26:29], v[162:165], v[202:205], v[26:29]
	v_mfma_f32_16x16x32_bf16 v[10:13], v[162:165], v[210:213], v[10:13]
	v_mfma_f32_16x16x32_bf16 v[14:17], v[146:149], v[210:213], v[14:17]
	v_mfma_f32_16x16x32_bf16 v[62:65], v[158:161], v[190:193], v[62:65]
	v_mfma_f32_16x16x32_bf16 v[58:61], v[166:169], v[190:193], v[58:61]
	v_mfma_f32_16x16x32_bf16 v[42:45], v[166:169], v[198:201], v[42:45]
	v_mfma_f32_16x16x32_bf16 v[46:49], v[158:161], v[198:201], v[46:49]
	v_mfma_f32_16x16x32_bf16 v[30:33], v[158:161], v[206:209], v[30:33]
	v_mfma_f32_16x16x32_bf16 v[26:29], v[166:169], v[206:209], v[26:29]
	v_mfma_f32_16x16x32_bf16 v[10:13], v[166:169], v[214:217], v[10:13]
	v_mfma_f32_16x16x32_bf16 v[14:17], v[158:161], v[214:217], v[14:17]
	s_setprio 0
	s_setprio 1
	v_mfma_f32_16x16x32_bf16 v[54:57], v[170:173], v[186:189], v[54:57]
	v_mfma_f32_16x16x32_bf16 v[50:53], v[178:181], v[186:189], v[50:53]
	v_mfma_f32_16x16x32_bf16 v[34:37], v[178:181], v[194:197], v[34:37]
	v_mfma_f32_16x16x32_bf16 v[38:41], v[170:173], v[194:197], v[38:41]
	v_mfma_f32_16x16x32_bf16 v[22:25], v[170:173], v[202:205], v[22:25]
	v_mfma_f32_16x16x32_bf16 v[18:21], v[178:181], v[202:205], v[18:21]
	v_mfma_f32_16x16x32_bf16 v[2:5], v[178:181], v[210:213], v[2:5]
	v_mfma_f32_16x16x32_bf16 v[6:9], v[170:173], v[210:213], v[6:9]
	v_mfma_f32_16x16x32_bf16 v[54:57], v[174:177], v[190:193], v[54:57]
	v_mfma_f32_16x16x32_bf16 v[50:53], v[182:185], v[190:193], v[50:53]
	v_mfma_f32_16x16x32_bf16 v[34:37], v[182:185], v[198:201], v[34:37]
	v_mfma_f32_16x16x32_bf16 v[38:41], v[174:177], v[198:201], v[38:41]
	v_mfma_f32_16x16x32_bf16 v[22:25], v[174:177], v[206:209], v[22:25]
	v_mfma_f32_16x16x32_bf16 v[18:21], v[182:185], v[206:209], v[18:21]
	v_mfma_f32_16x16x32_bf16 v[2:5], v[182:185], v[214:217], v[2:5]
	v_mfma_f32_16x16x32_bf16 v[6:9], v[174:177], v[214:217], v[6:9]
	s_setprio 0
	s_barrier
	s_add_i32 s53, 0, 0x18000
	v_add_u32_e32 v157, s53, v152
	s_add_i32 s54, 0, 0x1c000
	ds_read_b128 v[146:149], v157
	ds_read_b128 v[158:161], v157 offset:1024
	ds_read_b128 v[162:165], v157 offset:2048
	ds_read_b128 v[166:169], v157 offset:3072
	v_add_u32_e32 v157, s54, v152
	ds_read_b128 v[170:173], v157
	ds_read_b128 v[174:177], v157 offset:1024
	ds_read_b128 v[178:181], v157 offset:2048
	ds_read_b128 v[182:185], v157 offset:3072
	s_add_u32 s28, s28, 0x40000
	s_addc_u32 s29, s29, 0
	s_mov_b32 m0, s38
	v_lshl_add_u64 v[224:225], s[28:29], 0, v[130:131]
	ds_read_b128 v[186:189], v156 offset:32768
	ds_read_b128 v[190:193], v156 offset:33792
	ds_read_b128 v[194:197], v156 offset:34816
	ds_read_b128 v[198:201], v156 offset:35840
	ds_read_b128 v[202:205], v156 offset:36864
	ds_read_b128 v[206:209], v156 offset:37888
	ds_read_b128 v[210:213], v156 offset:38912
	ds_read_b128 v[214:217], v156 offset:39936
	global_load_lds_dwordx4 v[224:225], off
	v_lshl_add_u64 v[224:225], s[28:29], 0, v[134:135]
	s_mov_b32 m0, s39
	s_nop 0
	global_load_lds_dwordx4 v[224:225], off
	s_waitcnt vmcnt(8)
	s_waitcnt lgkmcnt(0)
	s_barrier
	s_setprio 1
	s_waitcnt lgkmcnt(0)
	v_mfma_f32_16x16x32_bf16 v[126:129], v[146:149], v[186:189], v[126:129]
	v_mfma_f32_16x16x32_bf16 v[122:125], v[162:165], v[186:189], v[122:125]
	v_mfma_f32_16x16x32_bf16 v[106:109], v[162:165], v[194:197], v[106:109]
	v_mfma_f32_16x16x32_bf16 v[110:113], v[146:149], v[194:197], v[110:113]
	v_mfma_f32_16x16x32_bf16 v[94:97], v[146:149], v[202:205], v[94:97]
	v_mfma_f32_16x16x32_bf16 v[90:93], v[162:165], v[202:205], v[90:93]
	v_mfma_f32_16x16x32_bf16 v[74:77], v[162:165], v[210:213], v[74:77]
	v_mfma_f32_16x16x32_bf16 v[78:81], v[146:149], v[210:213], v[78:81]
	v_mfma_f32_16x16x32_bf16 v[126:129], v[158:161], v[190:193], v[126:129]
	v_mfma_f32_16x16x32_bf16 v[122:125], v[166:169], v[190:193], v[122:125]
	v_mfma_f32_16x16x32_bf16 v[106:109], v[166:169], v[198:201], v[106:109]
	v_mfma_f32_16x16x32_bf16 v[110:113], v[158:161], v[198:201], v[110:113]
	v_mfma_f32_16x16x32_bf16 v[94:97], v[158:161], v[206:209], v[94:97]
	v_mfma_f32_16x16x32_bf16 v[90:93], v[166:169], v[206:209], v[90:93]
	v_mfma_f32_16x16x32_bf16 v[74:77], v[166:169], v[214:217], v[74:77]
	v_mfma_f32_16x16x32_bf16 v[78:81], v[158:161], v[214:217], v[78:81]
	s_setprio 0
	s_setprio 1
	v_mfma_f32_16x16x32_bf16 v[118:121], v[170:173], v[186:189], v[118:121]
	v_mfma_f32_16x16x32_bf16 v[114:117], v[178:181], v[186:189], v[114:117]
	v_mfma_f32_16x16x32_bf16 v[98:101], v[178:181], v[194:197], v[98:101]
	v_mfma_f32_16x16x32_bf16 v[102:105], v[170:173], v[194:197], v[102:105]
	v_mfma_f32_16x16x32_bf16 v[86:89], v[170:173], v[202:205], v[86:89]
	v_mfma_f32_16x16x32_bf16 v[82:85], v[178:181], v[202:205], v[82:85]
	v_mfma_f32_16x16x32_bf16 v[66:69], v[178:181], v[210:213], v[66:69]
	v_mfma_f32_16x16x32_bf16 v[70:73], v[170:173], v[210:213], v[70:73]
	v_mfma_f32_16x16x32_bf16 v[118:121], v[174:177], v[190:193], v[118:121]
	v_mfma_f32_16x16x32_bf16 v[114:117], v[182:185], v[190:193], v[114:117]
	v_mfma_f32_16x16x32_bf16 v[98:101], v[182:185], v[198:201], v[98:101]
	v_mfma_f32_16x16x32_bf16 v[102:105], v[174:177], v[198:201], v[102:105]
	v_mfma_f32_16x16x32_bf16 v[86:89], v[174:177], v[206:209], v[86:89]
	v_mfma_f32_16x16x32_bf16 v[82:85], v[182:185], v[206:209], v[82:85]
	v_mfma_f32_16x16x32_bf16 v[66:69], v[182:185], v[214:217], v[66:69]
	v_mfma_f32_16x16x32_bf16 v[70:73], v[174:177], v[214:217], v[70:73]
	s_setprio 0
	s_barrier
	s_add_i32 s28, s53, s36
	v_lshl_add_u64 v[150:151], v[150:151], 0, s[8:9]
	s_mov_b32 m0, s28
	ds_read_b128 v[186:189], v156 offset:49152
	ds_read_b128 v[190:193], v156 offset:50176
	ds_read_b128 v[194:197], v156 offset:51200
	ds_read_b128 v[198:201], v156 offset:52224
	ds_read_b128 v[202:205], v156 offset:53248
	ds_read_b128 v[206:209], v156 offset:54272
	ds_read_b128 v[210:213], v156 offset:55296
	ds_read_b128 v[214:217], v156 offset:56320
	global_load_lds_dwordx4 v[150:151], off
	s_add_i32 m0, s28, 0x2000
	s_add_u32 s26, s26, 0x40080
	v_lshl_add_u64 v[150:151], v[218:219], 0, s[8:9]
	s_addc_u32 s27, s27, 0
	s_add_i32 s28, s54, s36
	global_load_lds_dwordx4 v[150:151], off
	v_lshl_add_u64 v[150:151], s[26:27], 0, v[132:133]
	s_mov_b32 m0, s28
	s_nop 0
	global_load_lds_dwordx4 v[150:151], off
	v_lshl_add_u64 v[150:151], s[26:27], 0, v[136:137]
	s_add_i32 m0, s28, 0x2000
	s_nop 0
	global_load_lds_dwordx4 v[150:151], off
	v_lshl_add_u64 v[150:151], v[220:221], 0, s[8:9]
	s_mov_b32 m0, s41
	s_nop 0
	global_load_lds_dwordx4 v[150:151], off
	v_lshl_add_u64 v[150:151], v[222:223], 0, s[8:9]
	s_mov_b32 m0, s42
	s_nop 0
	global_load_lds_dwordx4 v[150:151], off
	s_waitcnt vmcnt(8)
	s_waitcnt lgkmcnt(0)
	s_barrier
	s_setprio 1
	s_waitcnt lgkmcnt(0)
	v_mfma_f32_16x16x32_bf16 v[62:65], v[146:149], v[186:189], v[62:65]
	v_mfma_f32_16x16x32_bf16 v[58:61], v[162:165], v[186:189], v[58:61]
	v_mfma_f32_16x16x32_bf16 v[42:45], v[162:165], v[194:197], v[42:45]
	v_mfma_f32_16x16x32_bf16 v[46:49], v[146:149], v[194:197], v[46:49]
	v_mfma_f32_16x16x32_bf16 v[30:33], v[146:149], v[202:205], v[30:33]
	v_mfma_f32_16x16x32_bf16 v[26:29], v[162:165], v[202:205], v[26:29]
	v_mfma_f32_16x16x32_bf16 v[10:13], v[162:165], v[210:213], v[10:13]
	v_mfma_f32_16x16x32_bf16 v[14:17], v[146:149], v[210:213], v[14:17]
	v_mfma_f32_16x16x32_bf16 v[62:65], v[158:161], v[190:193], v[62:65]
	v_mfma_f32_16x16x32_bf16 v[58:61], v[166:169], v[190:193], v[58:61]
	v_mfma_f32_16x16x32_bf16 v[42:45], v[166:169], v[198:201], v[42:45]
	v_mfma_f32_16x16x32_bf16 v[46:49], v[158:161], v[198:201], v[46:49]
	v_mfma_f32_16x16x32_bf16 v[30:33], v[158:161], v[206:209], v[30:33]
	v_mfma_f32_16x16x32_bf16 v[26:29], v[166:169], v[206:209], v[26:29]
	v_mfma_f32_16x16x32_bf16 v[10:13], v[166:169], v[214:217], v[10:13]
	v_mfma_f32_16x16x32_bf16 v[14:17], v[158:161], v[214:217], v[14:17]
	s_setprio 0
	s_setprio 1
	v_mfma_f32_16x16x32_bf16 v[54:57], v[170:173], v[186:189], v[54:57]
	v_mfma_f32_16x16x32_bf16 v[50:53], v[178:181], v[186:189], v[50:53]
	v_mfma_f32_16x16x32_bf16 v[34:37], v[178:181], v[194:197], v[34:37]
	v_mfma_f32_16x16x32_bf16 v[38:41], v[170:173], v[194:197], v[38:41]
	v_mfma_f32_16x16x32_bf16 v[22:25], v[170:173], v[202:205], v[22:25]
	v_mfma_f32_16x16x32_bf16 v[18:21], v[178:181], v[202:205], v[18:21]
	v_mfma_f32_16x16x32_bf16 v[2:5], v[178:181], v[210:213], v[2:5]
	v_mfma_f32_16x16x32_bf16 v[6:9], v[170:173], v[210:213], v[6:9]
	v_mfma_f32_16x16x32_bf16 v[54:57], v[174:177], v[190:193], v[54:57]
	v_mfma_f32_16x16x32_bf16 v[50:53], v[182:185], v[190:193], v[50:53]
	v_mfma_f32_16x16x32_bf16 v[34:37], v[182:185], v[198:201], v[34:37]
	v_mfma_f32_16x16x32_bf16 v[38:41], v[174:177], v[198:201], v[38:41]
	v_mfma_f32_16x16x32_bf16 v[22:25], v[174:177], v[206:209], v[22:25]
	v_mfma_f32_16x16x32_bf16 v[18:21], v[182:185], v[206:209], v[18:21]
	v_mfma_f32_16x16x32_bf16 v[2:5], v[182:185], v[214:217], v[2:5]
	v_mfma_f32_16x16x32_bf16 v[6:9], v[174:177], v[214:217], v[6:9]
	s_setprio 0
	s_barrier
	s_add_i32 s52, s52, 2
	s_add_u32 s24, s24, 0x100
	s_addc_u32 s25, s25, 0
	s_add_u32 s50, s50, 0x100
	s_addc_u32 s51, s51, 0
	s_cmp_gt_u32 s52, 13
	s_cbranch_scc0 .LBB0_556
	s_and_b64 vcc, exec, s[10:11]
	s_cbranch_vccz .LBB0_559
	s_barrier

.LBB0_635:
	ds_read_b128 v[152:155], v148
	ds_read_b128 v[156:159], v148 offset:1024
	ds_read_b128 v[160:163], v148 offset:2048
	ds_read_b128 v[164:167], v148 offset:3072
	ds_read_b128 v[168:171], v149
	ds_read_b128 v[172:175], v149 offset:1024
	ds_read_b128 v[176:179], v149 offset:2048
	ds_read_b128 v[180:183], v149 offset:3072
	s_add_u32 s34, s30, 0xfff80080
	s_addc_u32 s35, s31, -1
	s_cmp_eq_u32 s60, 28
	s_cselect_b32 s37, s25, s35
	s_cselect_b32 s36, s56, s34
	s_cselect_b32 s35, s23, s59
	s_cselect_b32 s34, s57, s58
	v_lshl_add_u64 v[216:217], s[30:31], 0, v[138:139]
	s_add_i32 m0, s21, 0xc000
	ds_read_b128 v[184:187], v150
	ds_read_b128 v[188:191], v150 offset:1024
	ds_read_b128 v[192:195], v150 offset:2048
	ds_read_b128 v[196:199], v150 offset:3072
	ds_read_b128 v[200:203], v150 offset:4096
	ds_read_b128 v[204:207], v150 offset:5120
	ds_read_b128 v[208:211], v150 offset:6144
	ds_read_b128 v[212:215], v150 offset:7168
	global_load_lds_dwordx4 v[216:217], off
	v_lshl_add_u64 v[216:217], s[30:31], 0, v[140:141]
	s_add_i32 m0, s21, 0xe000
	s_nop 0
	global_load_lds_dwordx4 v[216:217], off
	s_waitcnt vmcnt(8)
	s_waitcnt lgkmcnt(0)
	s_barrier
	s_setprio 1
	s_waitcnt lgkmcnt(0)
	v_mfma_f32_16x16x32_bf16 v[126:129], v[152:155], v[184:187], v[126:129]
	v_mfma_f32_16x16x32_bf16 v[122:125], v[160:163], v[184:187], v[122:125]
	v_mfma_f32_16x16x32_bf16 v[114:117], v[160:163], v[192:195], v[114:117]
	v_mfma_f32_16x16x32_bf16 v[118:121], v[152:155], v[192:195], v[118:121]
	v_mfma_f32_16x16x32_bf16 v[102:105], v[152:155], v[200:203], v[102:105]
	v_mfma_f32_16x16x32_bf16 v[98:101], v[160:163], v[200:203], v[98:101]
	v_mfma_f32_16x16x32_bf16 v[82:85], v[160:163], v[208:211], v[82:85]
	v_mfma_f32_16x16x32_bf16 v[86:89], v[152:155], v[208:211], v[86:89]
	v_mfma_f32_16x16x32_bf16 v[126:129], v[156:159], v[188:191], v[126:129]
	v_mfma_f32_16x16x32_bf16 v[122:125], v[164:167], v[188:191], v[122:125]
	v_mfma_f32_16x16x32_bf16 v[114:117], v[164:167], v[196:199], v[114:117]
	v_mfma_f32_16x16x32_bf16 v[118:121], v[156:159], v[196:199], v[118:121]
	v_mfma_f32_16x16x32_bf16 v[102:105], v[156:159], v[204:207], v[102:105]
	v_mfma_f32_16x16x32_bf16 v[98:101], v[164:167], v[204:207], v[98:101]
	v_mfma_f32_16x16x32_bf16 v[82:85], v[164:167], v[212:215], v[82:85]
	v_mfma_f32_16x16x32_bf16 v[86:89], v[156:159], v[212:215], v[86:89]
	s_setprio 0
	s_setprio 1
	v_mfma_f32_16x16x32_bf16 v[110:113], v[168:171], v[184:187], v[110:113]
	v_mfma_f32_16x16x32_bf16 v[106:109], v[176:179], v[184:187], v[106:109]
	v_mfma_f32_16x16x32_bf16 v[90:93], v[176:179], v[192:195], v[90:93]
	v_mfma_f32_16x16x32_bf16 v[94:97], v[168:171], v[192:195], v[94:97]
	v_mfma_f32_16x16x32_bf16 v[78:81], v[168:171], v[200:203], v[78:81]
	v_mfma_f32_16x16x32_bf16 v[74:77], v[176:179], v[200:203], v[74:77]
	v_mfma_f32_16x16x32_bf16 v[66:69], v[176:179], v[208:211], v[66:69]
	v_mfma_f32_16x16x32_bf16 v[70:73], v[168:171], v[208:211], v[70:73]
	v_mfma_f32_16x16x32_bf16 v[110:113], v[172:175], v[188:191], v[110:113]
	v_mfma_f32_16x16x32_bf16 v[106:109], v[180:183], v[188:191], v[106:109]
	v_mfma_f32_16x16x32_bf16 v[90:93], v[180:183], v[196:199], v[90:93]
	v_mfma_f32_16x16x32_bf16 v[94:97], v[172:175], v[196:199], v[94:97]
	v_mfma_f32_16x16x32_bf16 v[78:81], v[172:175], v[204:207], v[78:81]
	v_mfma_f32_16x16x32_bf16 v[74:77], v[180:183], v[204:207], v[74:77]
	v_mfma_f32_16x16x32_bf16 v[66:69], v[180:183], v[212:215], v[66:69]
	v_mfma_f32_16x16x32_bf16 v[70:73], v[172:175], v[212:215], v[70:73]
	s_setprio 0
	s_barrier
	s_add_i32 s61, s49, s40
	v_lshl_add_u64 v[216:217], s[34:35], 0, v[132:133]
	s_mov_b32 m0, s61
	ds_read_b128 v[184:187], v150 offset:16384
	ds_read_b128 v[188:191], v150 offset:17408
	ds_read_b128 v[192:195], v150 offset:18432
	ds_read_b128 v[196:199], v150 offset:19456
	ds_read_b128 v[200:203], v150 offset:20480
	ds_read_b128 v[204:207], v150 offset:21504
	ds_read_b128 v[208:211], v150 offset:22528
	ds_read_b128 v[212:215], v150 offset:23552
	global_load_lds_dwordx4 v[216:217], off
	s_add_i32 m0, s61, 0x2000
	s_add_u32 s62, s34, 0x80000
	v_lshl_add_u64 v[218:219], s[34:35], 0, v[136:137]
	s_addc_u32 s63, s35, 0
	s_add_i32 s61, s50, s40
	global_load_lds_dwordx4 v[218:219], off
	v_lshl_add_u64 v[220:221], s[62:63], 0, v[132:133]
	s_mov_b32 m0, s61
	v_lshl_add_u64 v[222:223], s[36:37], 0, v[134:135]
	global_load_lds_dwordx4 v[220:221], off
	v_lshl_add_u64 v[220:221], s[62:63], 0, v[136:137]
	s_add_i32 m0, s61, 0x2000
	s_nop 0
	global_load_lds_dwordx4 v[220:221], off
	v_lshl_add_u64 v[220:221], s[36:37], 0, v[130:131]
	s_mov_b32 m0, s21
	s_nop 0
	global_load_lds_dwordx4 v[220:221], off
	s_mov_b32 m0, s41
	s_nop 0
	global_load_lds_dwordx4 v[222:223], off
	s_waitcnt vmcnt(8)
	s_waitcnt lgkmcnt(0)
	s_barrier
	s_setprio 1
	s_waitcnt lgkmcnt(0)
	v_mfma_f32_16x16x32_bf16 v[62:65], v[152:155], v[184:187], v[62:65]
	v_mfma_f32_16x16x32_bf16 v[58:61], v[160:163], v[184:187], v[58:61]
	v_mfma_f32_16x16x32_bf16 v[50:53], v[160:163], v[192:195], v[50:53]
	v_mfma_f32_16x16x32_bf16 v[54:57], v[152:155], v[192:195], v[54:57]
	v_mfma_f32_16x16x32_bf16 v[38:41], v[152:155], v[200:203], v[38:41]
	v_mfma_f32_16x16x32_bf16 v[34:37], v[160:163], v[200:203], v[34:37]
	v_mfma_f32_16x16x32_bf16 v[18:21], v[160:163], v[208:211], v[18:21]
	v_mfma_f32_16x16x32_bf16 v[22:25], v[152:155], v[208:211], v[22:25]
	v_mfma_f32_16x16x32_bf16 v[62:65], v[156:159], v[188:191], v[62:65]
	v_mfma_f32_16x16x32_bf16 v[58:61], v[164:167], v[188:191], v[58:61]
	v_mfma_f32_16x16x32_bf16 v[50:53], v[164:167], v[196:199], v[50:53]
	v_mfma_f32_16x16x32_bf16 v[54:57], v[156:159], v[196:199], v[54:57]
	v_mfma_f32_16x16x32_bf16 v[38:41], v[156:159], v[204:207], v[38:41]
	v_mfma_f32_16x16x32_bf16 v[34:37], v[164:167], v[204:207], v[34:37]
	v_mfma_f32_16x16x32_bf16 v[18:21], v[164:167], v[212:215], v[18:21]
	v_mfma_f32_16x16x32_bf16 v[22:25], v[156:159], v[212:215], v[22:25]
	s_setprio 0
	s_setprio 1
	v_mfma_f32_16x16x32_bf16 v[46:49], v[168:171], v[184:187], v[46:49]
	v_mfma_f32_16x16x32_bf16 v[42:45], v[176:179], v[184:187], v[42:45]
	v_mfma_f32_16x16x32_bf16 v[26:29], v[176:179], v[192:195], v[26:29]
	v_mfma_f32_16x16x32_bf16 v[30:33], v[168:171], v[192:195], v[30:33]
	v_mfma_f32_16x16x32_bf16 v[14:17], v[168:171], v[200:203], v[14:17]
	v_mfma_f32_16x16x32_bf16 v[10:13], v[176:179], v[200:203], v[10:13]
	v_mfma_f32_16x16x32_bf16 v[2:5], v[176:179], v[208:211], v[2:5]
	v_mfma_f32_16x16x32_bf16 v[6:9], v[168:171], v[208:211], v[6:9]
	v_mfma_f32_16x16x32_bf16 v[46:49], v[172:175], v[188:191], v[46:49]
	v_mfma_f32_16x16x32_bf16 v[42:45], v[180:183], v[188:191], v[42:45]
	v_mfma_f32_16x16x32_bf16 v[26:29], v[180:183], v[196:199], v[26:29]
	v_mfma_f32_16x16x32_bf16 v[30:33], v[172:175], v[196:199], v[30:33]
	v_mfma_f32_16x16x32_bf16 v[14:17], v[172:175], v[204:207], v[14:17]
	v_mfma_f32_16x16x32_bf16 v[10:13], v[180:183], v[204:207], v[10:13]
	v_mfma_f32_16x16x32_bf16 v[2:5], v[180:183], v[212:215], v[2:5]
	v_mfma_f32_16x16x32_bf16 v[6:9], v[172:175], v[212:215], v[6:9]
	s_setprio 0
	s_barrier
	s_add_i32 s61, 0, 0x18000
	v_add_u32_e32 v151, s61, v146
	s_add_i32 s62, 0, 0x1c000
	ds_read_b128 v[152:155], v151
	ds_read_b128 v[156:159], v151 offset:1024
	ds_read_b128 v[160:163], v151 offset:2048
	ds_read_b128 v[164:167], v151 offset:3072
	v_add_u32_e32 v151, s62, v146
	ds_read_b128 v[168:171], v151
	ds_read_b128 v[172:175], v151 offset:1024
	ds_read_b128 v[176:179], v151 offset:2048
	ds_read_b128 v[180:183], v151 offset:3072
	s_add_u32 s36, s36, 0x80000
	s_addc_u32 s37, s37, 0
	s_mov_b32 m0, s42
	v_lshl_add_u64 v[224:225], s[36:37], 0, v[130:131]
	ds_read_b128 v[184:187], v150 offset:32768
	ds_read_b128 v[188:191], v150 offset:33792
	ds_read_b128 v[192:195], v150 offset:34816
	ds_read_b128 v[196:199], v150 offset:35840
	ds_read_b128 v[200:203], v150 offset:36864
	ds_read_b128 v[204:207], v150 offset:37888
	ds_read_b128 v[208:211], v150 offset:38912
	ds_read_b128 v[212:215], v150 offset:39936
	global_load_lds_dwordx4 v[224:225], off
	v_lshl_add_u64 v[224:225], s[36:37], 0, v[134:135]
	s_mov_b32 m0, s43
	s_nop 0
	global_load_lds_dwordx4 v[224:225], off
	s_waitcnt vmcnt(8)
	s_waitcnt lgkmcnt(0)
	s_barrier
	s_setprio 1
	s_waitcnt lgkmcnt(0)
	v_mfma_f32_16x16x32_bf16 v[126:129], v[152:155], v[184:187], v[126:129]
	v_mfma_f32_16x16x32_bf16 v[122:125], v[160:163], v[184:187], v[122:125]
	v_mfma_f32_16x16x32_bf16 v[114:117], v[160:163], v[192:195], v[114:117]
	v_mfma_f32_16x16x32_bf16 v[118:121], v[152:155], v[192:195], v[118:121]
	v_mfma_f32_16x16x32_bf16 v[102:105], v[152:155], v[200:203], v[102:105]
	v_mfma_f32_16x16x32_bf16 v[98:101], v[160:163], v[200:203], v[98:101]
	v_mfma_f32_16x16x32_bf16 v[82:85], v[160:163], v[208:211], v[82:85]
	v_mfma_f32_16x16x32_bf16 v[86:89], v[152:155], v[208:211], v[86:89]
	v_mfma_f32_16x16x32_bf16 v[126:129], v[156:159], v[188:191], v[126:129]
	v_mfma_f32_16x16x32_bf16 v[122:125], v[164:167], v[188:191], v[122:125]
	v_mfma_f32_16x16x32_bf16 v[114:117], v[164:167], v[196:199], v[114:117]
	v_mfma_f32_16x16x32_bf16 v[118:121], v[156:159], v[196:199], v[118:121]
	v_mfma_f32_16x16x32_bf16 v[102:105], v[156:159], v[204:207], v[102:105]
	v_mfma_f32_16x16x32_bf16 v[98:101], v[164:167], v[204:207], v[98:101]
	v_mfma_f32_16x16x32_bf16 v[82:85], v[164:167], v[212:215], v[82:85]
	v_mfma_f32_16x16x32_bf16 v[86:89], v[156:159], v[212:215], v[86:89]
	s_setprio 0
	s_setprio 1
	v_mfma_f32_16x16x32_bf16 v[110:113], v[168:171], v[184:187], v[110:113]
	v_mfma_f32_16x16x32_bf16 v[106:109], v[176:179], v[184:187], v[106:109]
	v_mfma_f32_16x16x32_bf16 v[90:93], v[176:179], v[192:195], v[90:93]
	v_mfma_f32_16x16x32_bf16 v[94:97], v[168:171], v[192:195], v[94:97]
	v_mfma_f32_16x16x32_bf16 v[78:81], v[168:171], v[200:203], v[78:81]
	v_mfma_f32_16x16x32_bf16 v[74:77], v[176:179], v[200:203], v[74:77]
	v_mfma_f32_16x16x32_bf16 v[66:69], v[176:179], v[208:211], v[66:69]
	v_mfma_f32_16x16x32_bf16 v[70:73], v[168:171], v[208:211], v[70:73]
	v_mfma_f32_16x16x32_bf16 v[110:113], v[172:175], v[188:191], v[110:113]
	v_mfma_f32_16x16x32_bf16 v[106:109], v[180:183], v[188:191], v[106:109]
	v_mfma_f32_16x16x32_bf16 v[90:93], v[180:183], v[196:199], v[90:93]
	v_mfma_f32_16x16x32_bf16 v[94:97], v[172:175], v[196:199], v[94:97]
	v_mfma_f32_16x16x32_bf16 v[78:81], v[172:175], v[204:207], v[78:81]
	v_mfma_f32_16x16x32_bf16 v[74:77], v[180:183], v[204:207], v[74:77]
	v_mfma_f32_16x16x32_bf16 v[66:69], v[180:183], v[212:215], v[66:69]
	v_mfma_f32_16x16x32_bf16 v[70:73], v[172:175], v[212:215], v[70:73]
	s_setprio 0
	s_barrier
	s_add_i32 s36, s61, s40
	v_lshl_add_u64 v[216:217], v[216:217], 0, s[10:11]
	s_mov_b32 m0, s36
	ds_read_b128 v[184:187], v150 offset:49152
	ds_read_b128 v[188:191], v150 offset:50176
	ds_read_b128 v[192:195], v150 offset:51200
	ds_read_b128 v[196:199], v150 offset:52224
	ds_read_b128 v[200:203], v150 offset:53248
	ds_read_b128 v[204:207], v150 offset:54272
	ds_read_b128 v[208:211], v150 offset:55296
	ds_read_b128 v[212:215], v150 offset:56320
	global_load_lds_dwordx4 v[216:217], off
	s_add_i32 m0, s36, 0x2000
	s_add_u32 s34, s34, 0x80080
	v_lshl_add_u64 v[216:217], v[218:219], 0, s[10:11]
	s_addc_u32 s35, s35, 0
	s_add_i32 s36, s62, s40
	global_load_lds_dwordx4 v[216:217], off
	v_lshl_add_u64 v[216:217], s[34:35], 0, v[132:133]
	s_mov_b32 m0, s36
	s_nop 0
	global_load_lds_dwordx4 v[216:217], off
	v_lshl_add_u64 v[216:217], s[34:35], 0, v[136:137]
	s_add_i32 m0, s36, 0x2000
	s_nop 0
	global_load_lds_dwordx4 v[216:217], off
	v_lshl_add_u64 v[216:217], v[220:221], 0, s[10:11]
	s_mov_b32 m0, s45
	s_nop 0
	global_load_lds_dwordx4 v[216:217], off
	v_lshl_add_u64 v[216:217], v[222:223], 0, s[10:11]
	s_mov_b32 m0, s46
	s_nop 0
	global_load_lds_dwordx4 v[216:217], off
	s_waitcnt vmcnt(8)
	s_waitcnt lgkmcnt(0)
	s_barrier
	s_setprio 1
	s_waitcnt lgkmcnt(0)
	v_mfma_f32_16x16x32_bf16 v[62:65], v[152:155], v[184:187], v[62:65]
	v_mfma_f32_16x16x32_bf16 v[58:61], v[160:163], v[184:187], v[58:61]
	v_mfma_f32_16x16x32_bf16 v[50:53], v[160:163], v[192:195], v[50:53]
	v_mfma_f32_16x16x32_bf16 v[54:57], v[152:155], v[192:195], v[54:57]
	v_mfma_f32_16x16x32_bf16 v[38:41], v[152:155], v[200:203], v[38:41]
	v_mfma_f32_16x16x32_bf16 v[34:37], v[160:163], v[200:203], v[34:37]
	v_mfma_f32_16x16x32_bf16 v[18:21], v[160:163], v[208:211], v[18:21]
	v_mfma_f32_16x16x32_bf16 v[22:25], v[152:155], v[208:211], v[22:25]
	v_mfma_f32_16x16x32_bf16 v[62:65], v[156:159], v[188:191], v[62:65]
	v_mfma_f32_16x16x32_bf16 v[58:61], v[164:167], v[188:191], v[58:61]
	v_mfma_f32_16x16x32_bf16 v[50:53], v[164:167], v[196:199], v[50:53]
	v_mfma_f32_16x16x32_bf16 v[54:57], v[156:159], v[196:199], v[54:57]
	v_mfma_f32_16x16x32_bf16 v[38:41], v[156:159], v[204:207], v[38:41]
	v_mfma_f32_16x16x32_bf16 v[34:37], v[164:167], v[204:207], v[34:37]
	v_mfma_f32_16x16x32_bf16 v[18:21], v[164:167], v[212:215], v[18:21]
	v_mfma_f32_16x16x32_bf16 v[22:25], v[156:159], v[212:215], v[22:25]
	s_setprio 0
	s_setprio 1
	v_mfma_f32_16x16x32_bf16 v[46:49], v[168:171], v[184:187], v[46:49]
	v_mfma_f32_16x16x32_bf16 v[42:45], v[176:179], v[184:187], v[42:45]
	v_mfma_f32_16x16x32_bf16 v[26:29], v[176:179], v[192:195], v[26:29]
	v_mfma_f32_16x16x32_bf16 v[30:33], v[168:171], v[192:195], v[30:33]
	v_mfma_f32_16x16x32_bf16 v[14:17], v[168:171], v[200:203], v[14:17]
	v_mfma_f32_16x16x32_bf16 v[10:13], v[176:179], v[200:203], v[10:13]
	v_mfma_f32_16x16x32_bf16 v[2:5], v[176:179], v[208:211], v[2:5]
	v_mfma_f32_16x16x32_bf16 v[6:9], v[168:171], v[208:211], v[6:9]
	v_mfma_f32_16x16x32_bf16 v[46:49], v[172:175], v[188:191], v[46:49]
	v_mfma_f32_16x16x32_bf16 v[42:45], v[180:183], v[188:191], v[42:45]
	v_mfma_f32_16x16x32_bf16 v[26:29], v[180:183], v[196:199], v[26:29]
	v_mfma_f32_16x16x32_bf16 v[30:33], v[172:175], v[196:199], v[30:33]
	v_mfma_f32_16x16x32_bf16 v[14:17], v[172:175], v[204:207], v[14:17]
	v_mfma_f32_16x16x32_bf16 v[10:13], v[180:183], v[204:207], v[10:13]
	v_mfma_f32_16x16x32_bf16 v[2:5], v[180:183], v[212:215], v[2:5]
	v_mfma_f32_16x16x32_bf16 v[6:9], v[172:175], v[212:215], v[6:9]
	s_setprio 0
	s_barrier
	s_add_i32 s60, s60, 2
	s_add_u32 s30, s30, 0x100
	s_addc_u32 s31, s31, 0
	s_add_u32 s58, s58, 0x100
	s_addc_u32 s59, s59, 0
	s_cmp_gt_u32 s60, 29
	s_cbranch_scc0 .LBB0_635
	s_and_b64 vcc, exec, s[12:13]
	s_cbranch_vccz .LBB0_638
	s_barrier

.LBB0_770:
	ds_read_b128 v[146:149], v156
	ds_read_b128 v[150:153], v156 offset:1024
	ds_read_b128 v[160:163], v156 offset:2048
	ds_read_b128 v[164:167], v156 offset:3072
	ds_read_b128 v[168:171], v157
	ds_read_b128 v[172:175], v157 offset:1024
	ds_read_b128 v[176:179], v157 offset:2048
	ds_read_b128 v[180:183], v157 offset:3072
	s_add_u32 s26, s24, 0xfff80080
	s_addc_u32 s27, s25, -1
	s_cmp_eq_u32 s52, 28
	s_cselect_b32 s29, s17, s27
	s_cselect_b32 s28, s48, s26
	s_cselect_b32 s27, s15, s51
	s_cselect_b32 s26, s49, s50
	v_lshl_add_u64 v[216:217], s[24:25], 0, v[138:139]
	s_add_i32 m0, s23, 0xc000
	ds_read_b128 v[184:187], v158
	ds_read_b128 v[188:191], v158 offset:1024
	ds_read_b128 v[192:195], v158 offset:2048
	ds_read_b128 v[196:199], v158 offset:3072
	ds_read_b128 v[200:203], v158 offset:4096
	ds_read_b128 v[204:207], v158 offset:5120
	ds_read_b128 v[208:211], v158 offset:6144
	ds_read_b128 v[212:215], v158 offset:7168
	global_load_lds_dwordx4 v[216:217], off
	v_lshl_add_u64 v[216:217], s[24:25], 0, v[140:141]
	s_add_i32 m0, s23, 0xe000
	s_nop 0
	global_load_lds_dwordx4 v[216:217], off
	s_waitcnt vmcnt(8)
	s_waitcnt lgkmcnt(0)
	s_barrier
	s_setprio 1
	s_waitcnt lgkmcnt(0)
	v_mfma_f32_16x16x32_bf16 v[126:129], v[146:149], v[184:187], v[126:129]
	v_mfma_f32_16x16x32_bf16 v[122:125], v[160:163], v[184:187], v[122:125]
	v_mfma_f32_16x16x32_bf16 v[106:109], v[160:163], v[192:195], v[106:109]
	v_mfma_f32_16x16x32_bf16 v[110:113], v[146:149], v[192:195], v[110:113]
	v_mfma_f32_16x16x32_bf16 v[94:97], v[146:149], v[200:203], v[94:97]
	v_mfma_f32_16x16x32_bf16 v[90:93], v[160:163], v[200:203], v[90:93]
	v_mfma_f32_16x16x32_bf16 v[74:77], v[160:163], v[208:211], v[74:77]
	v_mfma_f32_16x16x32_bf16 v[78:81], v[146:149], v[208:211], v[78:81]
	v_mfma_f32_16x16x32_bf16 v[126:129], v[150:153], v[188:191], v[126:129]
	v_mfma_f32_16x16x32_bf16 v[122:125], v[164:167], v[188:191], v[122:125]
	v_mfma_f32_16x16x32_bf16 v[106:109], v[164:167], v[196:199], v[106:109]
	v_mfma_f32_16x16x32_bf16 v[110:113], v[150:153], v[196:199], v[110:113]
	v_mfma_f32_16x16x32_bf16 v[94:97], v[150:153], v[204:207], v[94:97]
	v_mfma_f32_16x16x32_bf16 v[90:93], v[164:167], v[204:207], v[90:93]
	v_mfma_f32_16x16x32_bf16 v[74:77], v[164:167], v[212:215], v[74:77]
	v_mfma_f32_16x16x32_bf16 v[78:81], v[150:153], v[212:215], v[78:81]
	s_setprio 0
	s_setprio 1
	v_mfma_f32_16x16x32_bf16 v[118:121], v[168:171], v[184:187], v[118:121]
	v_mfma_f32_16x16x32_bf16 v[114:117], v[176:179], v[184:187], v[114:117]
	v_mfma_f32_16x16x32_bf16 v[98:101], v[176:179], v[192:195], v[98:101]
	v_mfma_f32_16x16x32_bf16 v[102:105], v[168:171], v[192:195], v[102:105]
	v_mfma_f32_16x16x32_bf16 v[86:89], v[168:171], v[200:203], v[86:89]
	v_mfma_f32_16x16x32_bf16 v[82:85], v[176:179], v[200:203], v[82:85]
	v_mfma_f32_16x16x32_bf16 v[66:69], v[176:179], v[208:211], v[66:69]
	v_mfma_f32_16x16x32_bf16 v[70:73], v[168:171], v[208:211], v[70:73]
	v_mfma_f32_16x16x32_bf16 v[118:121], v[172:175], v[188:191], v[118:121]
	v_mfma_f32_16x16x32_bf16 v[114:117], v[180:183], v[188:191], v[114:117]
	v_mfma_f32_16x16x32_bf16 v[98:101], v[180:183], v[196:199], v[98:101]
	v_mfma_f32_16x16x32_bf16 v[102:105], v[172:175], v[196:199], v[102:105]
	v_mfma_f32_16x16x32_bf16 v[86:89], v[172:175], v[204:207], v[86:89]
	v_mfma_f32_16x16x32_bf16 v[82:85], v[180:183], v[204:207], v[82:85]
	v_mfma_f32_16x16x32_bf16 v[66:69], v[180:183], v[212:215], v[66:69]
	v_mfma_f32_16x16x32_bf16 v[70:73], v[172:175], v[212:215], v[70:73]
	s_setprio 0
	s_barrier
	s_add_i32 s53, s44, s33
	v_lshl_add_u64 v[216:217], s[26:27], 0, v[134:135]
	s_mov_b32 m0, s53
	ds_read_b128 v[184:187], v158 offset:16384
	ds_read_b128 v[188:191], v158 offset:17408
	ds_read_b128 v[192:195], v158 offset:18432
	ds_read_b128 v[196:199], v158 offset:19456
	ds_read_b128 v[200:203], v158 offset:20480
	ds_read_b128 v[204:207], v158 offset:21504
	ds_read_b128 v[208:211], v158 offset:22528
	ds_read_b128 v[212:215], v158 offset:23552
	global_load_lds_dwordx4 v[216:217], off
	s_add_i32 m0, s53, 0x2000
	s_add_u32 s54, s26, 0x80000
	v_lshl_add_u64 v[218:219], s[26:27], 0, v[130:131]
	s_addc_u32 s55, s27, 0
	s_add_i32 s53, s45, s33
	global_load_lds_dwordx4 v[218:219], off
	v_lshl_add_u64 v[220:221], s[54:55], 0, v[134:135]
	s_mov_b32 m0, s53
	v_lshl_add_u64 v[222:223], s[28:29], 0, v[132:133]
	global_load_lds_dwordx4 v[220:221], off
	v_lshl_add_u64 v[220:221], s[54:55], 0, v[130:131]
	s_add_i32 m0, s53, 0x2000
	s_nop 0
	global_load_lds_dwordx4 v[220:221], off
	v_lshl_add_u64 v[220:221], s[28:29], 0, v[136:137]
	s_mov_b32 m0, s23
	s_nop 0
	global_load_lds_dwordx4 v[220:221], off
	s_mov_b32 m0, s36
	s_nop 0
	global_load_lds_dwordx4 v[222:223], off
	s_waitcnt vmcnt(8)
	s_waitcnt lgkmcnt(0)
	s_barrier
	s_setprio 1
	s_waitcnt lgkmcnt(0)
	v_mfma_f32_16x16x32_bf16 v[62:65], v[146:149], v[184:187], v[62:65]
	v_mfma_f32_16x16x32_bf16 v[58:61], v[160:163], v[184:187], v[58:61]
	v_mfma_f32_16x16x32_bf16 v[42:45], v[160:163], v[192:195], v[42:45]
	v_mfma_f32_16x16x32_bf16 v[46:49], v[146:149], v[192:195], v[46:49]
	v_mfma_f32_16x16x32_bf16 v[30:33], v[146:149], v[200:203], v[30:33]
	v_mfma_f32_16x16x32_bf16 v[26:29], v[160:163], v[200:203], v[26:29]
	v_mfma_f32_16x16x32_bf16 v[10:13], v[160:163], v[208:211], v[10:13]
	v_mfma_f32_16x16x32_bf16 v[14:17], v[146:149], v[208:211], v[14:17]
	v_mfma_f32_16x16x32_bf16 v[62:65], v[150:153], v[188:191], v[62:65]
	v_mfma_f32_16x16x32_bf16 v[58:61], v[164:167], v[188:191], v[58:61]
	v_mfma_f32_16x16x32_bf16 v[42:45], v[164:167], v[196:199], v[42:45]
	v_mfma_f32_16x16x32_bf16 v[46:49], v[150:153], v[196:199], v[46:49]
	v_mfma_f32_16x16x32_bf16 v[30:33], v[150:153], v[204:207], v[30:33]
	v_mfma_f32_16x16x32_bf16 v[26:29], v[164:167], v[204:207], v[26:29]
	v_mfma_f32_16x16x32_bf16 v[10:13], v[164:167], v[212:215], v[10:13]
	v_mfma_f32_16x16x32_bf16 v[14:17], v[150:153], v[212:215], v[14:17]
	s_setprio 0
	s_setprio 1
	v_mfma_f32_16x16x32_bf16 v[54:57], v[168:171], v[184:187], v[54:57]
	v_mfma_f32_16x16x32_bf16 v[50:53], v[176:179], v[184:187], v[50:53]
	v_mfma_f32_16x16x32_bf16 v[34:37], v[176:179], v[192:195], v[34:37]
	v_mfma_f32_16x16x32_bf16 v[38:41], v[168:171], v[192:195], v[38:41]
	v_mfma_f32_16x16x32_bf16 v[22:25], v[168:171], v[200:203], v[22:25]
	v_mfma_f32_16x16x32_bf16 v[18:21], v[176:179], v[200:203], v[18:21]
	v_mfma_f32_16x16x32_bf16 v[2:5], v[176:179], v[208:211], v[2:5]
	v_mfma_f32_16x16x32_bf16 v[6:9], v[168:171], v[208:211], v[6:9]
	v_mfma_f32_16x16x32_bf16 v[54:57], v[172:175], v[188:191], v[54:57]
	v_mfma_f32_16x16x32_bf16 v[50:53], v[180:183], v[188:191], v[50:53]
	v_mfma_f32_16x16x32_bf16 v[34:37], v[180:183], v[196:199], v[34:37]
	v_mfma_f32_16x16x32_bf16 v[38:41], v[172:175], v[196:199], v[38:41]
	v_mfma_f32_16x16x32_bf16 v[22:25], v[172:175], v[204:207], v[22:25]
	v_mfma_f32_16x16x32_bf16 v[18:21], v[180:183], v[204:207], v[18:21]
	v_mfma_f32_16x16x32_bf16 v[2:5], v[180:183], v[212:215], v[2:5]
	v_mfma_f32_16x16x32_bf16 v[6:9], v[172:175], v[212:215], v[6:9]
	s_setprio 0
	s_barrier
	s_add_i32 s53, 0, 0x18000
	v_add_u32_e32 v159, s53, v154
	s_add_i32 s54, 0, 0x1c000
	ds_read_b128 v[146:149], v159
	ds_read_b128 v[150:153], v159 offset:1024
	ds_read_b128 v[160:163], v159 offset:2048
	ds_read_b128 v[164:167], v159 offset:3072
	v_add_u32_e32 v159, s54, v154
	ds_read_b128 v[168:171], v159
	ds_read_b128 v[172:175], v159 offset:1024
	ds_read_b128 v[176:179], v159 offset:2048
	ds_read_b128 v[180:183], v159 offset:3072
	s_add_u32 s28, s28, 0x80000
	s_addc_u32 s29, s29, 0
	s_mov_b32 m0, s37
	v_lshl_add_u64 v[224:225], s[28:29], 0, v[136:137]
	ds_read_b128 v[184:187], v158 offset:32768
	ds_read_b128 v[188:191], v158 offset:33792
	ds_read_b128 v[192:195], v158 offset:34816
	ds_read_b128 v[196:199], v158 offset:35840
	ds_read_b128 v[200:203], v158 offset:36864
	ds_read_b128 v[204:207], v158 offset:37888
	ds_read_b128 v[208:211], v158 offset:38912
	ds_read_b128 v[212:215], v158 offset:39936
	global_load_lds_dwordx4 v[224:225], off
	v_lshl_add_u64 v[224:225], s[28:29], 0, v[132:133]
	s_mov_b32 m0, s38
	s_nop 0
	global_load_lds_dwordx4 v[224:225], off
	s_waitcnt vmcnt(8)
	s_waitcnt lgkmcnt(0)
	s_barrier
	s_setprio 1
	s_waitcnt lgkmcnt(0)
	v_mfma_f32_16x16x32_bf16 v[126:129], v[146:149], v[184:187], v[126:129]
	v_mfma_f32_16x16x32_bf16 v[122:125], v[160:163], v[184:187], v[122:125]
	v_mfma_f32_16x16x32_bf16 v[106:109], v[160:163], v[192:195], v[106:109]
	v_mfma_f32_16x16x32_bf16 v[110:113], v[146:149], v[192:195], v[110:113]
	v_mfma_f32_16x16x32_bf16 v[94:97], v[146:149], v[200:203], v[94:97]
	v_mfma_f32_16x16x32_bf16 v[90:93], v[160:163], v[200:203], v[90:93]
	v_mfma_f32_16x16x32_bf16 v[74:77], v[160:163], v[208:211], v[74:77]
	v_mfma_f32_16x16x32_bf16 v[78:81], v[146:149], v[208:211], v[78:81]
	v_mfma_f32_16x16x32_bf16 v[126:129], v[150:153], v[188:191], v[126:129]
	v_mfma_f32_16x16x32_bf16 v[122:125], v[164:167], v[188:191], v[122:125]
	v_mfma_f32_16x16x32_bf16 v[106:109], v[164:167], v[196:199], v[106:109]
	v_mfma_f32_16x16x32_bf16 v[110:113], v[150:153], v[196:199], v[110:113]
	v_mfma_f32_16x16x32_bf16 v[94:97], v[150:153], v[204:207], v[94:97]
	v_mfma_f32_16x16x32_bf16 v[90:93], v[164:167], v[204:207], v[90:93]
	v_mfma_f32_16x16x32_bf16 v[74:77], v[164:167], v[212:215], v[74:77]
	v_mfma_f32_16x16x32_bf16 v[78:81], v[150:153], v[212:215], v[78:81]
	s_setprio 0
	s_setprio 1
	v_mfma_f32_16x16x32_bf16 v[118:121], v[168:171], v[184:187], v[118:121]
	v_mfma_f32_16x16x32_bf16 v[114:117], v[176:179], v[184:187], v[114:117]
	v_mfma_f32_16x16x32_bf16 v[98:101], v[176:179], v[192:195], v[98:101]
	v_mfma_f32_16x16x32_bf16 v[102:105], v[168:171], v[192:195], v[102:105]
	v_mfma_f32_16x16x32_bf16 v[86:89], v[168:171], v[200:203], v[86:89]
	v_mfma_f32_16x16x32_bf16 v[82:85], v[176:179], v[200:203], v[82:85]
	v_mfma_f32_16x16x32_bf16 v[66:69], v[176:179], v[208:211], v[66:69]
	v_mfma_f32_16x16x32_bf16 v[70:73], v[168:171], v[208:211], v[70:73]
	v_mfma_f32_16x16x32_bf16 v[118:121], v[172:175], v[188:191], v[118:121]
	v_mfma_f32_16x16x32_bf16 v[114:117], v[180:183], v[188:191], v[114:117]
	v_mfma_f32_16x16x32_bf16 v[98:101], v[180:183], v[196:199], v[98:101]
	v_mfma_f32_16x16x32_bf16 v[102:105], v[172:175], v[196:199], v[102:105]
	v_mfma_f32_16x16x32_bf16 v[86:89], v[172:175], v[204:207], v[86:89]
	v_mfma_f32_16x16x32_bf16 v[82:85], v[180:183], v[204:207], v[82:85]
	v_mfma_f32_16x16x32_bf16 v[66:69], v[180:183], v[212:215], v[66:69]
	v_mfma_f32_16x16x32_bf16 v[70:73], v[172:175], v[212:215], v[70:73]
	s_setprio 0
	s_barrier
	s_add_i32 s28, s53, s33
	v_lshl_add_u64 v[216:217], v[216:217], 0, s[10:11]
	s_mov_b32 m0, s28
	ds_read_b128 v[184:187], v158 offset:49152
	ds_read_b128 v[188:191], v158 offset:50176
	ds_read_b128 v[192:195], v158 offset:51200
	ds_read_b128 v[196:199], v158 offset:52224
	ds_read_b128 v[200:203], v158 offset:53248
	ds_read_b128 v[204:207], v158 offset:54272
	ds_read_b128 v[208:211], v158 offset:55296
	ds_read_b128 v[212:215], v158 offset:56320
	global_load_lds_dwordx4 v[216:217], off
	s_add_i32 m0, s28, 0x2000
	s_add_u32 s26, s26, 0x80080
	v_lshl_add_u64 v[216:217], v[218:219], 0, s[10:11]
	s_addc_u32 s27, s27, 0
	s_add_i32 s28, s54, s33
	global_load_lds_dwordx4 v[216:217], off
	v_lshl_add_u64 v[216:217], s[26:27], 0, v[134:135]
	s_mov_b32 m0, s28
	s_nop 0
	global_load_lds_dwordx4 v[216:217], off
	v_lshl_add_u64 v[216:217], s[26:27], 0, v[130:131]
	s_add_i32 m0, s28, 0x2000
	s_nop 0
	global_load_lds_dwordx4 v[216:217], off
	v_lshl_add_u64 v[216:217], v[220:221], 0, s[10:11]
	s_mov_b32 m0, s40
	s_nop 0
	global_load_lds_dwordx4 v[216:217], off
	v_lshl_add_u64 v[216:217], v[222:223], 0, s[10:11]
	s_mov_b32 m0, s41
	s_nop 0
	global_load_lds_dwordx4 v[216:217], off
	s_waitcnt vmcnt(8)
	s_waitcnt lgkmcnt(0)
	s_barrier
	s_setprio 1
	s_waitcnt lgkmcnt(0)
	v_mfma_f32_16x16x32_bf16 v[62:65], v[146:149], v[184:187], v[62:65]
	v_mfma_f32_16x16x32_bf16 v[58:61], v[160:163], v[184:187], v[58:61]
	v_mfma_f32_16x16x32_bf16 v[42:45], v[160:163], v[192:195], v[42:45]
	v_mfma_f32_16x16x32_bf16 v[46:49], v[146:149], v[192:195], v[46:49]
	v_mfma_f32_16x16x32_bf16 v[30:33], v[146:149], v[200:203], v[30:33]
	v_mfma_f32_16x16x32_bf16 v[26:29], v[160:163], v[200:203], v[26:29]
	v_mfma_f32_16x16x32_bf16 v[10:13], v[160:163], v[208:211], v[10:13]
	v_mfma_f32_16x16x32_bf16 v[14:17], v[146:149], v[208:211], v[14:17]
	v_mfma_f32_16x16x32_bf16 v[62:65], v[150:153], v[188:191], v[62:65]
	v_mfma_f32_16x16x32_bf16 v[58:61], v[164:167], v[188:191], v[58:61]
	v_mfma_f32_16x16x32_bf16 v[42:45], v[164:167], v[196:199], v[42:45]
	v_mfma_f32_16x16x32_bf16 v[46:49], v[150:153], v[196:199], v[46:49]
	v_mfma_f32_16x16x32_bf16 v[30:33], v[150:153], v[204:207], v[30:33]
	v_mfma_f32_16x16x32_bf16 v[26:29], v[164:167], v[204:207], v[26:29]
	v_mfma_f32_16x16x32_bf16 v[10:13], v[164:167], v[212:215], v[10:13]
	v_mfma_f32_16x16x32_bf16 v[14:17], v[150:153], v[212:215], v[14:17]
	s_setprio 0
	s_setprio 1
	v_mfma_f32_16x16x32_bf16 v[54:57], v[168:171], v[184:187], v[54:57]
	v_mfma_f32_16x16x32_bf16 v[50:53], v[176:179], v[184:187], v[50:53]
	v_mfma_f32_16x16x32_bf16 v[34:37], v[176:179], v[192:195], v[34:37]
	v_mfma_f32_16x16x32_bf16 v[38:41], v[168:171], v[192:195], v[38:41]
	v_mfma_f32_16x16x32_bf16 v[22:25], v[168:171], v[200:203], v[22:25]
	v_mfma_f32_16x16x32_bf16 v[18:21], v[176:179], v[200:203], v[18:21]
	v_mfma_f32_16x16x32_bf16 v[2:5], v[176:179], v[208:211], v[2:5]
	v_mfma_f32_16x16x32_bf16 v[6:9], v[168:171], v[208:211], v[6:9]
	v_mfma_f32_16x16x32_bf16 v[54:57], v[172:175], v[188:191], v[54:57]
	v_mfma_f32_16x16x32_bf16 v[50:53], v[180:183], v[188:191], v[50:53]
	v_mfma_f32_16x16x32_bf16 v[34:37], v[180:183], v[196:199], v[34:37]
	v_mfma_f32_16x16x32_bf16 v[38:41], v[172:175], v[196:199], v[38:41]
	v_mfma_f32_16x16x32_bf16 v[22:25], v[172:175], v[204:207], v[22:25]
	v_mfma_f32_16x16x32_bf16 v[18:21], v[180:183], v[204:207], v[18:21]
	v_mfma_f32_16x16x32_bf16 v[2:5], v[180:183], v[212:215], v[2:5]
	v_mfma_f32_16x16x32_bf16 v[6:9], v[172:175], v[212:215], v[6:9]
	s_setprio 0
	s_barrier
	s_add_i32 s52, s52, 2
	s_add_u32 s24, s24, 0x100
	s_addc_u32 s25, s25, 0
	s_add_u32 s50, s50, 0x100
	s_addc_u32 s51, s51, 0
	s_cmp_gt_u32 s52, 29
	s_cbranch_scc0 .LBB0_770
	s_and_b64 vcc, exec, s[12:13]
	s_cbranch_vccz .LBB0_773
	s_barrier

.LBB0_853:
	ds_read_b128 v[150:153], v147
	ds_read_b128 v[154:157], v147 offset:1024
	ds_read_b128 v[158:161], v147 offset:2048
	ds_read_b128 v[162:165], v147 offset:3072
	ds_read_b128 v[166:169], v148
	ds_read_b128 v[170:173], v148 offset:1024
	ds_read_b128 v[174:177], v148 offset:2048
	ds_read_b128 v[178:181], v148 offset:3072
	s_add_u32 s24, s22, 0xffea0080
	s_addc_u32 s25, s23, -1
	s_cmpk_eq_i32 s56, 0x54
	s_cselect_b32 s27, s1, s25
	s_cselect_b32 s26, s0, s24
	s_cselect_b32 s25, s21, s55
	s_cselect_b32 s24, s20, s54
	v_lshl_add_u64 v[214:215], s[22:23], 0, v[136:137]
	s_add_i32 m0, s35, 0xc000
	ds_read_b128 v[182:185], v149
	ds_read_b128 v[186:189], v149 offset:1024
	ds_read_b128 v[190:193], v149 offset:2048
	ds_read_b128 v[194:197], v149 offset:3072
	ds_read_b128 v[198:201], v149 offset:4096
	ds_read_b128 v[202:205], v149 offset:5120
	ds_read_b128 v[206:209], v149 offset:6144
	ds_read_b128 v[210:213], v149 offset:7168
	global_load_lds_dwordx4 v[214:215], off
	v_lshl_add_u64 v[214:215], s[22:23], 0, v[138:139]
	s_add_i32 m0, s35, 0xe000
	s_nop 0
	global_load_lds_dwordx4 v[214:215], off
	s_waitcnt vmcnt(8)
	s_waitcnt lgkmcnt(0)
	s_barrier
	s_setprio 1
	s_waitcnt lgkmcnt(0)
	v_mfma_f32_16x16x32_bf16 v[124:127], v[150:153], v[182:185], v[124:127]
	v_mfma_f32_16x16x32_bf16 v[120:123], v[158:161], v[182:185], v[120:123]
	v_mfma_f32_16x16x32_bf16 v[112:115], v[158:161], v[190:193], v[112:115]
	v_mfma_f32_16x16x32_bf16 v[116:119], v[150:153], v[190:193], v[116:119]
	v_mfma_f32_16x16x32_bf16 v[100:103], v[150:153], v[198:201], v[100:103]
	v_mfma_f32_16x16x32_bf16 v[96:99], v[158:161], v[198:201], v[96:99]
	v_mfma_f32_16x16x32_bf16 v[80:83], v[158:161], v[206:209], v[80:83]
	v_mfma_f32_16x16x32_bf16 v[84:87], v[150:153], v[206:209], v[84:87]
	v_mfma_f32_16x16x32_bf16 v[124:127], v[154:157], v[186:189], v[124:127]
	v_mfma_f32_16x16x32_bf16 v[120:123], v[162:165], v[186:189], v[120:123]
	v_mfma_f32_16x16x32_bf16 v[112:115], v[162:165], v[194:197], v[112:115]
	v_mfma_f32_16x16x32_bf16 v[116:119], v[154:157], v[194:197], v[116:119]
	v_mfma_f32_16x16x32_bf16 v[100:103], v[154:157], v[202:205], v[100:103]
	v_mfma_f32_16x16x32_bf16 v[96:99], v[162:165], v[202:205], v[96:99]
	v_mfma_f32_16x16x32_bf16 v[80:83], v[162:165], v[210:213], v[80:83]
	v_mfma_f32_16x16x32_bf16 v[84:87], v[154:157], v[210:213], v[84:87]
	s_setprio 0
	s_setprio 1
	v_mfma_f32_16x16x32_bf16 v[108:111], v[166:169], v[182:185], v[108:111]
	v_mfma_f32_16x16x32_bf16 v[104:107], v[174:177], v[182:185], v[104:107]
	v_mfma_f32_16x16x32_bf16 v[88:91], v[174:177], v[190:193], v[88:91]
	v_mfma_f32_16x16x32_bf16 v[92:95], v[166:169], v[190:193], v[92:95]
	v_mfma_f32_16x16x32_bf16 v[76:79], v[166:169], v[198:201], v[76:79]
	v_mfma_f32_16x16x32_bf16 v[72:75], v[174:177], v[198:201], v[72:75]
	v_mfma_f32_16x16x32_bf16 v[64:67], v[174:177], v[206:209], v[64:67]
	v_mfma_f32_16x16x32_bf16 v[68:71], v[166:169], v[206:209], v[68:71]
	v_mfma_f32_16x16x32_bf16 v[108:111], v[170:173], v[186:189], v[108:111]
	v_mfma_f32_16x16x32_bf16 v[104:107], v[178:181], v[186:189], v[104:107]
	v_mfma_f32_16x16x32_bf16 v[88:91], v[178:181], v[194:197], v[88:91]
	v_mfma_f32_16x16x32_bf16 v[92:95], v[170:173], v[194:197], v[92:95]
	v_mfma_f32_16x16x32_bf16 v[76:79], v[170:173], v[202:205], v[76:79]
	v_mfma_f32_16x16x32_bf16 v[72:75], v[178:181], v[202:205], v[72:75]
	v_mfma_f32_16x16x32_bf16 v[64:67], v[178:181], v[210:213], v[64:67]
	v_mfma_f32_16x16x32_bf16 v[68:71], v[170:173], v[210:213], v[68:71]
	s_setprio 0
	s_barrier
	s_add_i32 s57, s44, s34
	v_lshl_add_u64 v[214:215], s[24:25], 0, v[130:131]
	s_mov_b32 m0, s57
	ds_read_b128 v[182:185], v149 offset:16384
	ds_read_b128 v[186:189], v149 offset:17408
	ds_read_b128 v[190:193], v149 offset:18432
	ds_read_b128 v[194:197], v149 offset:19456
	ds_read_b128 v[198:201], v149 offset:20480
	ds_read_b128 v[202:205], v149 offset:21504
	ds_read_b128 v[206:209], v149 offset:22528
	ds_read_b128 v[210:213], v149 offset:23552
	global_load_lds_dwordx4 v[214:215], off
	s_add_i32 m0, s57, 0x2000
	s_add_u32 s58, s24, 0x160000
	v_lshl_add_u64 v[216:217], s[24:25], 0, v[134:135]
	s_addc_u32 s59, s25, 0
	s_add_i32 s57, s45, s34
	global_load_lds_dwordx4 v[216:217], off
	v_lshl_add_u64 v[218:219], s[58:59], 0, v[130:131]
	s_mov_b32 m0, s57
	v_lshl_add_u64 v[220:221], s[26:27], 0, v[132:133]
	global_load_lds_dwordx4 v[218:219], off
	v_lshl_add_u64 v[218:219], s[58:59], 0, v[134:135]
	s_add_i32 m0, s57, 0x2000
	s_nop 0
	global_load_lds_dwordx4 v[218:219], off
	v_lshl_add_u64 v[218:219], s[26:27], 0, v[128:129]
	s_mov_b32 m0, s35
	s_nop 0
	global_load_lds_dwordx4 v[218:219], off
	s_mov_b32 m0, s36
	s_nop 0
	global_load_lds_dwordx4 v[220:221], off
	s_waitcnt vmcnt(8)
	s_waitcnt lgkmcnt(0)
	s_barrier
	s_setprio 1
	s_waitcnt lgkmcnt(0)
	v_mfma_f32_16x16x32_bf16 v[60:63], v[150:153], v[182:185], v[60:63]
	v_mfma_f32_16x16x32_bf16 v[56:59], v[158:161], v[182:185], v[56:59]
	v_mfma_f32_16x16x32_bf16 v[48:51], v[158:161], v[190:193], v[48:51]
	v_mfma_f32_16x16x32_bf16 v[52:55], v[150:153], v[190:193], v[52:55]
	v_mfma_f32_16x16x32_bf16 v[36:39], v[150:153], v[198:201], v[36:39]
	v_mfma_f32_16x16x32_bf16 v[32:35], v[158:161], v[198:201], v[32:35]
	v_mfma_f32_16x16x32_bf16 v[16:19], v[158:161], v[206:209], v[16:19]
	v_mfma_f32_16x16x32_bf16 v[20:23], v[150:153], v[206:209], v[20:23]
	v_mfma_f32_16x16x32_bf16 v[60:63], v[154:157], v[186:189], v[60:63]
	v_mfma_f32_16x16x32_bf16 v[56:59], v[162:165], v[186:189], v[56:59]
	v_mfma_f32_16x16x32_bf16 v[48:51], v[162:165], v[194:197], v[48:51]
	v_mfma_f32_16x16x32_bf16 v[52:55], v[154:157], v[194:197], v[52:55]
	v_mfma_f32_16x16x32_bf16 v[36:39], v[154:157], v[202:205], v[36:39]
	v_mfma_f32_16x16x32_bf16 v[32:35], v[162:165], v[202:205], v[32:35]
	v_mfma_f32_16x16x32_bf16 v[16:19], v[162:165], v[210:213], v[16:19]
	v_mfma_f32_16x16x32_bf16 v[20:23], v[154:157], v[210:213], v[20:23]
	s_setprio 0
	s_setprio 1
	v_mfma_f32_16x16x32_bf16 v[44:47], v[166:169], v[182:185], v[44:47]
	v_mfma_f32_16x16x32_bf16 v[40:43], v[174:177], v[182:185], v[40:43]
	v_mfma_f32_16x16x32_bf16 v[24:27], v[174:177], v[190:193], v[24:27]
	v_mfma_f32_16x16x32_bf16 v[28:31], v[166:169], v[190:193], v[28:31]
	v_mfma_f32_16x16x32_bf16 v[12:15], v[166:169], v[198:201], v[12:15]
	v_mfma_f32_16x16x32_bf16 v[8:11], v[174:177], v[198:201], v[8:11]
	v_mfma_f32_16x16x32_bf16 v[0:3], v[174:177], v[206:209], v[0:3]
	v_mfma_f32_16x16x32_bf16 v[4:7], v[166:169], v[206:209], v[4:7]
	v_mfma_f32_16x16x32_bf16 v[44:47], v[170:173], v[186:189], v[44:47]
	v_mfma_f32_16x16x32_bf16 v[40:43], v[178:181], v[186:189], v[40:43]
	v_mfma_f32_16x16x32_bf16 v[24:27], v[178:181], v[194:197], v[24:27]
	v_mfma_f32_16x16x32_bf16 v[28:31], v[170:173], v[194:197], v[28:31]
	v_mfma_f32_16x16x32_bf16 v[12:15], v[170:173], v[202:205], v[12:15]
	v_mfma_f32_16x16x32_bf16 v[8:11], v[178:181], v[202:205], v[8:11]
	v_mfma_f32_16x16x32_bf16 v[0:3], v[178:181], v[210:213], v[0:3]
	v_mfma_f32_16x16x32_bf16 v[4:7], v[170:173], v[210:213], v[4:7]
	s_setprio 0
	s_barrier
	s_add_i32 s57, 0, 0x18000
	s_add_i32 s58, 0, 0x1c000
	v_add_u32_e32 v162, s57, v145
	v_add_u32_e32 v178, s58, v145
	ds_read_b128 v[150:153], v162
	ds_read_b128 v[154:157], v162 offset:1024
	ds_read_b128 v[158:161], v162 offset:2048
	ds_read_b128 v[162:165], v162 offset:3072
	ds_read_b128 v[166:169], v178
	ds_read_b128 v[170:173], v178 offset:1024
	ds_read_b128 v[174:177], v178 offset:2048
	ds_read_b128 v[178:181], v178 offset:3072
	s_add_u32 s26, s26, 0x160000
	s_addc_u32 s27, s27, 0
	s_mov_b32 m0, s37
	v_lshl_add_u64 v[222:223], s[26:27], 0, v[128:129]
	ds_read_b128 v[182:185], v149 offset:32768
	ds_read_b128 v[186:189], v149 offset:33792
	ds_read_b128 v[190:193], v149 offset:34816
	ds_read_b128 v[194:197], v149 offset:35840
	ds_read_b128 v[198:201], v149 offset:36864
	ds_read_b128 v[202:205], v149 offset:37888
	ds_read_b128 v[206:209], v149 offset:38912
	ds_read_b128 v[210:213], v149 offset:39936
	global_load_lds_dwordx4 v[222:223], off
	v_lshl_add_u64 v[222:223], s[26:27], 0, v[132:133]
	s_mov_b32 m0, s38
	s_nop 0
	global_load_lds_dwordx4 v[222:223], off
	s_waitcnt vmcnt(8)
	s_waitcnt lgkmcnt(0)
	s_barrier
	s_setprio 1
	s_waitcnt lgkmcnt(0)
	v_mfma_f32_16x16x32_bf16 v[124:127], v[150:153], v[182:185], v[124:127]
	v_mfma_f32_16x16x32_bf16 v[120:123], v[158:161], v[182:185], v[120:123]
	v_mfma_f32_16x16x32_bf16 v[112:115], v[158:161], v[190:193], v[112:115]
	v_mfma_f32_16x16x32_bf16 v[116:119], v[150:153], v[190:193], v[116:119]
	v_mfma_f32_16x16x32_bf16 v[100:103], v[150:153], v[198:201], v[100:103]
	v_mfma_f32_16x16x32_bf16 v[96:99], v[158:161], v[198:201], v[96:99]
	v_mfma_f32_16x16x32_bf16 v[80:83], v[158:161], v[206:209], v[80:83]
	v_mfma_f32_16x16x32_bf16 v[84:87], v[150:153], v[206:209], v[84:87]
	v_mfma_f32_16x16x32_bf16 v[124:127], v[154:157], v[186:189], v[124:127]
	v_mfma_f32_16x16x32_bf16 v[120:123], v[162:165], v[186:189], v[120:123]
	v_mfma_f32_16x16x32_bf16 v[112:115], v[162:165], v[194:197], v[112:115]
	v_mfma_f32_16x16x32_bf16 v[116:119], v[154:157], v[194:197], v[116:119]
	v_mfma_f32_16x16x32_bf16 v[100:103], v[154:157], v[202:205], v[100:103]
	v_mfma_f32_16x16x32_bf16 v[96:99], v[162:165], v[202:205], v[96:99]
	v_mfma_f32_16x16x32_bf16 v[80:83], v[162:165], v[210:213], v[80:83]
	v_mfma_f32_16x16x32_bf16 v[84:87], v[154:157], v[210:213], v[84:87]
	s_setprio 0
	s_setprio 1
	v_mfma_f32_16x16x32_bf16 v[108:111], v[166:169], v[182:185], v[108:111]
	v_mfma_f32_16x16x32_bf16 v[104:107], v[174:177], v[182:185], v[104:107]
	v_mfma_f32_16x16x32_bf16 v[88:91], v[174:177], v[190:193], v[88:91]
	v_mfma_f32_16x16x32_bf16 v[92:95], v[166:169], v[190:193], v[92:95]
	v_mfma_f32_16x16x32_bf16 v[76:79], v[166:169], v[198:201], v[76:79]
	v_mfma_f32_16x16x32_bf16 v[72:75], v[174:177], v[198:201], v[72:75]
	v_mfma_f32_16x16x32_bf16 v[64:67], v[174:177], v[206:209], v[64:67]
	v_mfma_f32_16x16x32_bf16 v[68:71], v[166:169], v[206:209], v[68:71]
	v_mfma_f32_16x16x32_bf16 v[108:111], v[170:173], v[186:189], v[108:111]
	v_mfma_f32_16x16x32_bf16 v[104:107], v[178:181], v[186:189], v[104:107]
	v_mfma_f32_16x16x32_bf16 v[88:91], v[178:181], v[194:197], v[88:91]
	v_mfma_f32_16x16x32_bf16 v[92:95], v[170:173], v[194:197], v[92:95]
	v_mfma_f32_16x16x32_bf16 v[76:79], v[170:173], v[202:205], v[76:79]
	v_mfma_f32_16x16x32_bf16 v[72:75], v[178:181], v[202:205], v[72:75]
	v_mfma_f32_16x16x32_bf16 v[64:67], v[178:181], v[210:213], v[64:67]
	v_mfma_f32_16x16x32_bf16 v[68:71], v[170:173], v[210:213], v[68:71]
	s_setprio 0
	s_barrier
	s_add_i32 s26, s57, s34
	v_lshl_add_u64 v[214:215], v[214:215], 0, s[8:9]
	s_mov_b32 m0, s26
	ds_read_b128 v[182:185], v149 offset:49152
	ds_read_b128 v[186:189], v149 offset:50176
	ds_read_b128 v[190:193], v149 offset:51200
	ds_read_b128 v[194:197], v149 offset:52224
	ds_read_b128 v[198:201], v149 offset:53248
	ds_read_b128 v[202:205], v149 offset:54272
	ds_read_b128 v[206:209], v149 offset:55296
	ds_read_b128 v[210:213], v149 offset:56320
	global_load_lds_dwordx4 v[214:215], off
	s_add_i32 m0, s26, 0x2000
	s_add_u32 s24, s24, 0x160080
	v_lshl_add_u64 v[214:215], v[216:217], 0, s[8:9]
	s_addc_u32 s25, s25, 0
	s_add_i32 s26, s58, s34
	global_load_lds_dwordx4 v[214:215], off
	v_lshl_add_u64 v[214:215], s[24:25], 0, v[130:131]
	s_mov_b32 m0, s26
	s_nop 0
	global_load_lds_dwordx4 v[214:215], off
	v_lshl_add_u64 v[214:215], s[24:25], 0, v[134:135]
	s_add_i32 m0, s26, 0x2000
	s_nop 0
	global_load_lds_dwordx4 v[214:215], off
	v_lshl_add_u64 v[214:215], v[218:219], 0, s[8:9]
	s_mov_b32 m0, s40
	s_nop 0
	global_load_lds_dwordx4 v[214:215], off
	v_lshl_add_u64 v[214:215], v[220:221], 0, s[8:9]
	s_mov_b32 m0, s41
	s_nop 0
	global_load_lds_dwordx4 v[214:215], off
	s_waitcnt vmcnt(8)
	s_waitcnt lgkmcnt(0)
	s_barrier
	s_setprio 1
	s_waitcnt lgkmcnt(0)
	v_mfma_f32_16x16x32_bf16 v[60:63], v[150:153], v[182:185], v[60:63]
	v_mfma_f32_16x16x32_bf16 v[56:59], v[158:161], v[182:185], v[56:59]
	v_mfma_f32_16x16x32_bf16 v[48:51], v[158:161], v[190:193], v[48:51]
	v_mfma_f32_16x16x32_bf16 v[52:55], v[150:153], v[190:193], v[52:55]
	v_mfma_f32_16x16x32_bf16 v[36:39], v[150:153], v[198:201], v[36:39]
	v_mfma_f32_16x16x32_bf16 v[32:35], v[158:161], v[198:201], v[32:35]
	v_mfma_f32_16x16x32_bf16 v[16:19], v[158:161], v[206:209], v[16:19]
	v_mfma_f32_16x16x32_bf16 v[20:23], v[150:153], v[206:209], v[20:23]
	v_mfma_f32_16x16x32_bf16 v[60:63], v[154:157], v[186:189], v[60:63]
	v_mfma_f32_16x16x32_bf16 v[56:59], v[162:165], v[186:189], v[56:59]
	v_mfma_f32_16x16x32_bf16 v[48:51], v[162:165], v[194:197], v[48:51]
	v_mfma_f32_16x16x32_bf16 v[52:55], v[154:157], v[194:197], v[52:55]
	v_mfma_f32_16x16x32_bf16 v[36:39], v[154:157], v[202:205], v[36:39]
	v_mfma_f32_16x16x32_bf16 v[32:35], v[162:165], v[202:205], v[32:35]
	v_mfma_f32_16x16x32_bf16 v[16:19], v[162:165], v[210:213], v[16:19]
	v_mfma_f32_16x16x32_bf16 v[20:23], v[154:157], v[210:213], v[20:23]
	s_setprio 0
	s_setprio 1
	v_mfma_f32_16x16x32_bf16 v[44:47], v[166:169], v[182:185], v[44:47]
	v_mfma_f32_16x16x32_bf16 v[40:43], v[174:177], v[182:185], v[40:43]
	v_mfma_f32_16x16x32_bf16 v[24:27], v[174:177], v[190:193], v[24:27]
	v_mfma_f32_16x16x32_bf16 v[28:31], v[166:169], v[190:193], v[28:31]
	v_mfma_f32_16x16x32_bf16 v[12:15], v[166:169], v[198:201], v[12:15]
	v_mfma_f32_16x16x32_bf16 v[8:11], v[174:177], v[198:201], v[8:11]
	v_mfma_f32_16x16x32_bf16 v[0:3], v[174:177], v[206:209], v[0:3]
	v_mfma_f32_16x16x32_bf16 v[4:7], v[166:169], v[206:209], v[4:7]
	v_mfma_f32_16x16x32_bf16 v[44:47], v[170:173], v[186:189], v[44:47]
	v_mfma_f32_16x16x32_bf16 v[40:43], v[178:181], v[186:189], v[40:43]
	v_mfma_f32_16x16x32_bf16 v[24:27], v[178:181], v[194:197], v[24:27]
	v_mfma_f32_16x16x32_bf16 v[28:31], v[170:173], v[194:197], v[28:31]
	v_mfma_f32_16x16x32_bf16 v[12:15], v[170:173], v[202:205], v[12:15]
	v_mfma_f32_16x16x32_bf16 v[8:11], v[178:181], v[202:205], v[8:11]
	v_mfma_f32_16x16x32_bf16 v[0:3], v[178:181], v[210:213], v[0:3]
	v_mfma_f32_16x16x32_bf16 v[4:7], v[170:173], v[210:213], v[4:7]
	s_setprio 0
	s_barrier
	s_add_i32 s56, s56, 2
	s_add_u32 s22, s22, 0x100
	s_addc_u32 s23, s23, 0
	s_add_u32 s54, s54, 0x100
	s_addc_u32 s55, s55, 0
	s_cmpk_gt_u32 s56, 0x55
	s_cbranch_scc0 .LBB0_853
	s_and_b64 vcc, exec, s[10:11]
	s_cbranch_vccz .LBB0_856
	s_barrier
